# S4 priority skew limited to the first half of step A (waves 4-7 get s_setprio 1 only long enough to desynchronise the two waves of a SIMD, then both run at equal priority)
# speedup vs baseline: 1.0096x; 1.0096x over previous
.Ls4_noprio:
	v_readlane_b32 s0, v248, 20
	v_readlane_b32 s4, v248, 2
	v_readlane_b32 s5, v248, 17
	s_lshl_b32 s0, s0, 3
	s_add_i32 s0, s0, s1
	s_add_i32 s72, s72, s0
	s_lshr_b32 s1, s72, 4
	s_mov_b32 s3, 0x24300000
	s_cmp_eq_u32 s1, 2
	s_cselect_b32 s2, s3, 0x26000000
	s_cmp_lg_u32 s1, 1
	s_cselect_b32 s1, s2, 0x1d000000
	s_cmp_gt_u32 s72, 15
	s_cselect_b32 s1, s1, 0x1ed00000
	s_add_u32 s1, s70, s1
	s_addc_u32 s2, s71, 0
	s_lshl_b32 s0, s0, 6
	s_and_b32 s0, s0, 0x3c0
	s_add_i32 s0, s0, s85
	s_mul_hi_i32 s3, s0, 0x7400
	s_mulk_i32 s0, 0x7400
	s_add_u32 s6, s1, s0
	s_addc_u32 s7, s2, s3
	v_and_b32_e32 v20, 15, v1
	v_lshl_add_u32 v138, v20, 2, s4
	v_or_b32_e32 v139, 32, v1
	v_cmp_lt_u32_e64 s[2:3], 31, v1
	v_and_b32_e32 v154, 31, v1
	v_add_u32_e32 v154, 1, v154
	v_lshrrev_b32_e32 v155, 2, v154
	v_and_b32_e32 v154, 3, v154
	v_lshlrev_b32_e32 v20, 3, v155
	v_sub_u32_e32 v20, 0x104, v20
	v_mul_u32_u24_e32 v20, v155, v20
	v_lshlrev_b32_e32 v21, 2, v155
	v_sub_u32_e32 v21, 64, v21
	v_mul_u32_u24_e32 v21, v154, v21
	v_add_u32_e32 v20, v20, v21
	v_lshrrev_b32_e32 v21, 5, v1
	v_add_u32_e32 v20, v20, v21
	v_subrev_u32_e32 v20, 32, v20
	v_lshl_add_u32 v152, v20, 2, s4
	v_subrev_u32_e32 v153, 36, v1
	v_cndmask_b32_e64 v153, v1, v153, s[2:3]
	ds_read_b32 v226, v152 offset:0
	ds_read_b32 v227, v152 offset:8
	ds_read_b32 v228, v152 offset:16
	ds_read_b32 v229, v152 offset:24
	ds_read_b32 v230, v152 offset:32
	ds_read_b32 v231, v152 offset:40
	ds_read_b32 v232, v152 offset:48
	ds_read_b32 v233, v152 offset:56
	ds_read_b32 v234, v152 offset:64
	ds_read_b32 v235, v152 offset:72
	ds_read_b32 v236, v152 offset:80
	ds_read_b32 v237, v152 offset:88
	ds_read_b32 v238, v152 offset:96
	ds_read_b32 v239, v152 offset:104
	ds_read_b32 v240, v152 offset:112
	ds_read_b32 v241, v152 offset:120
	ds_read_b32 v148, v138 offset:8432
	v_cmp_eq_u32_e32 vcc, 63, v139
	s_nop 1
	v_cndmask_b32_e64 v134, 0, 1.0, vcc
	ds_read_b32 v144, v138 offset:8416
	s_waitcnt lgkmcnt(2)
	v_cmp_eq_u32_e32 vcc, 62, v139
	s_nop 1
	v_cndmask_b32_e64 v130, 0, 1.0, vcc
	v_mov_b32_e32 v129, v134
	ds_read_b32 v140, v138 offset:8400
	s_waitcnt lgkmcnt(2)
	v_cmp_eq_u32_e32 vcc, 61, v139
	v_mul_f32_dpp v133, -v148, v129 row_newbcast:3 row_mask:0xf bank_mask:0xf
	s_nop 0
	v_cndmask_b32_e64 v134, 0, 1.0, vcc
	v_add_f32_e32 v128, v130, v133
	ds_read_b32 v148, v138 offset:8384
	s_waitcnt lgkmcnt(2)
	v_cmp_eq_u32_e32 vcc, 60, v139
	v_mul_f32_dpp v137, -v144, v129 row_newbcast:3 row_mask:0xf bank_mask:0xf
	v_mul_f32_dpp v136, -v144, v128 row_newbcast:2 row_mask:0xf bank_mask:0xf
	v_cndmask_b32_e64 v130, 0, 1.0, vcc
	v_add_f32_e32 v21, v136, v137
	v_add_f32_e32 v127, v134, v21
	ds_read_b32 v144, v138 offset:8352
	s_waitcnt lgkmcnt(2)
	v_cmp_eq_u32_e32 vcc, 59, v139
	v_mul_f32_dpp v132, -v140, v128 row_newbcast:2 row_mask:0xf bank_mask:0xf
	v_mul_f32_dpp v133, -v140, v129 row_newbcast:3 row_mask:0xf bank_mask:0xf
	v_mul_f32_dpp v131, -v140, v127 row_newbcast:1 row_mask:0xf bank_mask:0xf
	v_cndmask_b32_e64 v134, 0, 1.0, vcc
	v_add_f32_e32 v20, v130, v131
	v_add_f32_e32 v21, v132, v133
	v_add_f32_e32 v126, v20, v21
	ds_read_b32 v140, v138 offset:8320
	s_waitcnt lgkmcnt(2)
	v_cmp_eq_u32_e32 vcc, 58, v139
	v_mul_f32_dpp v135, -v148, v127 row_newbcast:1 row_mask:0xf bank_mask:0xf
	v_mul_f32_dpp v136, -v148, v128 row_newbcast:2 row_mask:0xf bank_mask:0xf
	v_mul_f32_dpp v137, -v148, v129 row_newbcast:3 row_mask:0xf bank_mask:0xf
	v_fmac_f32_dpp v134, -v148, v126 row_newbcast:0 row_mask:0xf bank_mask:0xf
	v_cndmask_b32_e64 v130, 0, 1.0, vcc
	v_add_f32_e32 v20, v134, v135
	v_add_f32_e32 v21, v136, v137
	v_add_f32_e32 v125, v20, v21
	ds_read_b32 v148, v138 offset:8288
	s_waitcnt lgkmcnt(2)
	v_cmp_eq_u32_e32 vcc, 57, v139
	v_fmac_f32_dpp v130, -v144, v126 row_newbcast:4 row_mask:0xf bank_mask:0xf
	v_mul_f32_dpp v131, -v144, v127 row_newbcast:5 row_mask:0xf bank_mask:0xf
	v_mul_f32_dpp v132, -v144, v128 row_newbcast:6 row_mask:0xf bank_mask:0xf
	v_mul_f32_dpp v133, -v144, v125 row_newbcast:3 row_mask:0xf bank_mask:0xf
	s_nop 1
	v_fmac_f32_dpp v133, -v144, v129 row_newbcast:7 row_mask:0xf bank_mask:0xf
	v_cndmask_b32_e64 v134, 0, 1.0, vcc
	v_add_f32_e32 v20, v130, v131
	v_add_f32_e32 v21, v132, v133
	v_add_f32_e32 v124, v20, v21
	ds_read_b32 v144, v138 offset:8256
	s_waitcnt lgkmcnt(2)
	v_cmp_eq_u32_e32 vcc, 56, v139
	v_mul_f32_dpp v137, -v140, v125 row_newbcast:3 row_mask:0xf bank_mask:0xf
	v_fmac_f32_dpp v134, -v140, v126 row_newbcast:4 row_mask:0xf bank_mask:0xf
	v_mul_f32_dpp v135, -v140, v127 row_newbcast:5 row_mask:0xf bank_mask:0xf
	v_mul_f32_dpp v136, -v140, v124 row_newbcast:2 row_mask:0xf bank_mask:0xf
	v_fmac_f32_dpp v137, -v140, v129 row_newbcast:7 row_mask:0xf bank_mask:0xf
	s_nop 0
	v_fmac_f32_dpp v136, -v140, v128 row_newbcast:6 row_mask:0xf bank_mask:0xf
	v_cndmask_b32_e64 v130, 0, 1.0, vcc
	v_add_f32_e32 v20, v134, v135
	v_add_f32_e32 v21, v136, v137
	v_add_f32_e32 v123, v20, v21
	ds_read_b32 v140, v138 offset:8208
	s_waitcnt lgkmcnt(2)
	v_cmp_eq_u32_e32 vcc, 55, v139
	v_mul_f32_dpp v132, -v148, v124 row_newbcast:2 row_mask:0xf bank_mask:0xf
	v_mul_f32_dpp v133, -v148, v125 row_newbcast:3 row_mask:0xf bank_mask:0xf
	v_fmac_f32_dpp v130, -v148, v126 row_newbcast:4 row_mask:0xf bank_mask:0xf
	v_mul_f32_dpp v131, -v148, v123 row_newbcast:1 row_mask:0xf bank_mask:0xf
	v_fmac_f32_dpp v132, -v148, v128 row_newbcast:6 row_mask:0xf bank_mask:0xf
	v_fmac_f32_dpp v133, -v148, v129 row_newbcast:7 row_mask:0xf bank_mask:0xf
	v_fmac_f32_dpp v131, -v148, v127 row_newbcast:5 row_mask:0xf bank_mask:0xf
	v_cndmask_b32_e64 v134, 0, 1.0, vcc
	v_add_f32_e32 v20, v130, v131
	v_add_f32_e32 v21, v132, v133
	v_add_f32_e32 v122, v20, v21
	ds_read_b32 v148, v138 offset:8160
	s_waitcnt lgkmcnt(2)
	v_cmp_eq_u32_e32 vcc, 54, v139
	v_mul_f32_dpp v135, -v144, v123 row_newbcast:1 row_mask:0xf bank_mask:0xf
	v_mul_f32_dpp v136, -v144, v124 row_newbcast:2 row_mask:0xf bank_mask:0xf
	v_mul_f32_dpp v137, -v144, v125 row_newbcast:3 row_mask:0xf bank_mask:0xf
	v_fmac_f32_dpp v134, -v144, v122 row_newbcast:0 row_mask:0xf bank_mask:0xf
	v_fmac_f32_dpp v135, -v144, v127 row_newbcast:5 row_mask:0xf bank_mask:0xf
	v_fmac_f32_dpp v136, -v144, v128 row_newbcast:6 row_mask:0xf bank_mask:0xf
	v_fmac_f32_dpp v137, -v144, v129 row_newbcast:7 row_mask:0xf bank_mask:0xf
	v_fmac_f32_dpp v134, -v144, v126 row_newbcast:4 row_mask:0xf bank_mask:0xf
	v_cndmask_b32_e64 v130, 0, 1.0, vcc
	v_add_f32_e32 v20, v134, v135
	v_add_f32_e32 v21, v136, v137
	v_add_f32_e32 v121, v20, v21
	ds_read_b32 v144, v138 offset:8112
	s_waitcnt lgkmcnt(2)
	v_cmp_eq_u32_e32 vcc, 53, v139
	v_fmac_f32_dpp v130, -v140, v122 row_newbcast:4 row_mask:0xf bank_mask:0xf
	v_mul_f32_dpp v131, -v140, v123 row_newbcast:5 row_mask:0xf bank_mask:0xf
	v_mul_f32_dpp v132, -v140, v124 row_newbcast:6 row_mask:0xf bank_mask:0xf
	v_mul_f32_dpp v133, -v140, v121 row_newbcast:3 row_mask:0xf bank_mask:0xf
	v_fmac_f32_dpp v130, -v140, v126 row_newbcast:8 row_mask:0xf bank_mask:0xf
	v_fmac_f32_dpp v131, -v140, v127 row_newbcast:9 row_mask:0xf bank_mask:0xf
	v_fmac_f32_dpp v132, -v140, v128 row_newbcast:10 row_mask:0xf bank_mask:0xf
	v_fmac_f32_dpp v133, -v140, v125 row_newbcast:7 row_mask:0xf bank_mask:0xf
	s_nop 1
	v_fmac_f32_dpp v133, -v140, v129 row_newbcast:11 row_mask:0xf bank_mask:0xf
	v_cndmask_b32_e64 v134, 0, 1.0, vcc
	v_add_f32_e32 v20, v130, v131
	v_add_f32_e32 v21, v132, v133
	v_add_f32_e32 v120, v20, v21
	ds_read_b32 v140, v138 offset:8064
	s_waitcnt lgkmcnt(2)
	v_cmp_eq_u32_e32 vcc, 52, v139
	v_mul_f32_dpp v137, -v148, v121 row_newbcast:3 row_mask:0xf bank_mask:0xf
	v_fmac_f32_dpp v134, -v148, v122 row_newbcast:4 row_mask:0xf bank_mask:0xf
	v_mul_f32_dpp v135, -v148, v123 row_newbcast:5 row_mask:0xf bank_mask:0xf
	v_mul_f32_dpp v136, -v148, v120 row_newbcast:2 row_mask:0xf bank_mask:0xf
	v_fmac_f32_dpp v137, -v148, v125 row_newbcast:7 row_mask:0xf bank_mask:0xf
	v_fmac_f32_dpp v134, -v148, v126 row_newbcast:8 row_mask:0xf bank_mask:0xf
	v_fmac_f32_dpp v135, -v148, v127 row_newbcast:9 row_mask:0xf bank_mask:0xf
	v_fmac_f32_dpp v136, -v148, v124 row_newbcast:6 row_mask:0xf bank_mask:0xf
	v_fmac_f32_dpp v137, -v148, v129 row_newbcast:11 row_mask:0xf bank_mask:0xf
	s_nop 0
	v_fmac_f32_dpp v136, -v148, v128 row_newbcast:10 row_mask:0xf bank_mask:0xf
	v_cndmask_b32_e64 v130, 0, 1.0, vcc
	v_add_f32_e32 v20, v134, v135
	v_add_f32_e32 v21, v136, v137
	v_add_f32_e32 v119, v20, v21
	ds_read_b32 v148, v138 offset:8000
	s_waitcnt lgkmcnt(2)
	v_cmp_eq_u32_e32 vcc, 51, v139
	v_mul_f32_dpp v132, -v144, v120 row_newbcast:2 row_mask:0xf bank_mask:0xf
	v_mul_f32_dpp v133, -v144, v121 row_newbcast:3 row_mask:0xf bank_mask:0xf
	v_fmac_f32_dpp v130, -v144, v122 row_newbcast:4 row_mask:0xf bank_mask:0xf
	v_mul_f32_dpp v131, -v144, v119 row_newbcast:1 row_mask:0xf bank_mask:0xf
	v_fmac_f32_dpp v132, -v144, v124 row_newbcast:6 row_mask:0xf bank_mask:0xf
	v_fmac_f32_dpp v133, -v144, v125 row_newbcast:7 row_mask:0xf bank_mask:0xf
	v_fmac_f32_dpp v130, -v144, v126 row_newbcast:8 row_mask:0xf bank_mask:0xf
	v_fmac_f32_dpp v131, -v144, v123 row_newbcast:5 row_mask:0xf bank_mask:0xf
	v_fmac_f32_dpp v132, -v144, v128 row_newbcast:10 row_mask:0xf bank_mask:0xf
	v_fmac_f32_dpp v133, -v144, v129 row_newbcast:11 row_mask:0xf bank_mask:0xf
	v_fmac_f32_dpp v131, -v144, v127 row_newbcast:9 row_mask:0xf bank_mask:0xf
	v_cndmask_b32_e64 v134, 0, 1.0, vcc
	v_add_f32_e32 v20, v130, v131
	v_add_f32_e32 v21, v132, v133
	v_add_f32_e32 v118, v20, v21
	ds_read_b32 v144, v138 offset:7936
	s_waitcnt lgkmcnt(2)
	v_cmp_eq_u32_e32 vcc, 50, v139
	v_mul_f32_dpp v135, -v140, v119 row_newbcast:1 row_mask:0xf bank_mask:0xf
	v_mul_f32_dpp v136, -v140, v120 row_newbcast:2 row_mask:0xf bank_mask:0xf
	v_mul_f32_dpp v137, -v140, v121 row_newbcast:3 row_mask:0xf bank_mask:0xf
	v_fmac_f32_dpp v134, -v140, v118 row_newbcast:0 row_mask:0xf bank_mask:0xf
	v_fmac_f32_dpp v135, -v140, v123 row_newbcast:5 row_mask:0xf bank_mask:0xf
	v_fmac_f32_dpp v136, -v140, v124 row_newbcast:6 row_mask:0xf bank_mask:0xf
	v_fmac_f32_dpp v137, -v140, v125 row_newbcast:7 row_mask:0xf bank_mask:0xf
	v_fmac_f32_dpp v134, -v140, v122 row_newbcast:4 row_mask:0xf bank_mask:0xf
	v_fmac_f32_dpp v135, -v140, v127 row_newbcast:9 row_mask:0xf bank_mask:0xf
	v_fmac_f32_dpp v136, -v140, v128 row_newbcast:10 row_mask:0xf bank_mask:0xf
	v_fmac_f32_dpp v137, -v140, v129 row_newbcast:11 row_mask:0xf bank_mask:0xf
	v_fmac_f32_dpp v134, -v140, v126 row_newbcast:8 row_mask:0xf bank_mask:0xf
	v_cndmask_b32_e64 v130, 0, 1.0, vcc
	v_add_f32_e32 v20, v134, v135
	v_add_f32_e32 v21, v136, v137
	v_add_f32_e32 v117, v20, v21
	ds_read_b32 v140, v138 offset:7872
	s_waitcnt lgkmcnt(2)
	v_cmp_eq_u32_e32 vcc, 49, v139
	v_fmac_f32_dpp v130, -v148, v118 row_newbcast:4 row_mask:0xf bank_mask:0xf
	v_mul_f32_dpp v131, -v148, v119 row_newbcast:5 row_mask:0xf bank_mask:0xf
	v_mul_f32_dpp v132, -v148, v120 row_newbcast:6 row_mask:0xf bank_mask:0xf
	v_mul_f32_dpp v133, -v148, v117 row_newbcast:3 row_mask:0xf bank_mask:0xf
	v_fmac_f32_dpp v130, -v148, v122 row_newbcast:8 row_mask:0xf bank_mask:0xf
	v_fmac_f32_dpp v131, -v148, v123 row_newbcast:9 row_mask:0xf bank_mask:0xf
	v_fmac_f32_dpp v132, -v148, v124 row_newbcast:10 row_mask:0xf bank_mask:0xf
	v_fmac_f32_dpp v133, -v148, v121 row_newbcast:7 row_mask:0xf bank_mask:0xf
	v_fmac_f32_dpp v130, -v148, v126 row_newbcast:12 row_mask:0xf bank_mask:0xf
	v_fmac_f32_dpp v131, -v148, v127 row_newbcast:13 row_mask:0xf bank_mask:0xf
	v_fmac_f32_dpp v132, -v148, v128 row_newbcast:14 row_mask:0xf bank_mask:0xf
	v_fmac_f32_dpp v133, -v148, v125 row_newbcast:11 row_mask:0xf bank_mask:0xf
	s_nop 1
	v_fmac_f32_dpp v133, -v148, v129 row_newbcast:15 row_mask:0xf bank_mask:0xf
	v_cndmask_b32_e64 v134, 0, 1.0, vcc
	v_add_f32_e32 v20, v130, v131
	v_add_f32_e32 v21, v132, v133
	v_add_f32_e32 v116, v20, v21
	ds_read_b32 v148, v138 offset:7808
	s_waitcnt lgkmcnt(2)
	v_cmp_eq_u32_e32 vcc, 48, v139
	v_mul_f32_dpp v137, -v144, v117 row_newbcast:3 row_mask:0xf bank_mask:0xf
	v_fmac_f32_dpp v134, -v144, v118 row_newbcast:4 row_mask:0xf bank_mask:0xf
	v_mul_f32_dpp v135, -v144, v119 row_newbcast:5 row_mask:0xf bank_mask:0xf
	v_mul_f32_dpp v136, -v144, v116 row_newbcast:2 row_mask:0xf bank_mask:0xf
	v_fmac_f32_dpp v137, -v144, v121 row_newbcast:7 row_mask:0xf bank_mask:0xf
	v_fmac_f32_dpp v134, -v144, v122 row_newbcast:8 row_mask:0xf bank_mask:0xf
	v_fmac_f32_dpp v135, -v144, v123 row_newbcast:9 row_mask:0xf bank_mask:0xf
	v_fmac_f32_dpp v136, -v144, v120 row_newbcast:6 row_mask:0xf bank_mask:0xf
	v_fmac_f32_dpp v137, -v144, v125 row_newbcast:11 row_mask:0xf bank_mask:0xf
	v_fmac_f32_dpp v134, -v144, v126 row_newbcast:12 row_mask:0xf bank_mask:0xf
	v_fmac_f32_dpp v135, -v144, v127 row_newbcast:13 row_mask:0xf bank_mask:0xf
	v_fmac_f32_dpp v136, -v144, v124 row_newbcast:10 row_mask:0xf bank_mask:0xf
	v_fmac_f32_dpp v137, -v144, v129 row_newbcast:15 row_mask:0xf bank_mask:0xf
	s_nop 0
	v_fmac_f32_dpp v136, -v144, v128 row_newbcast:14 row_mask:0xf bank_mask:0xf
	v_cndmask_b32_e64 v130, 0, 1.0, vcc
	v_add_f32_e32 v20, v134, v135
	v_add_f32_e32 v21, v136, v137
	v_add_f32_e32 v115, v20, v21
	ds_read_b32 v144, v138 offset:7728
	ds_read_b32 v145, v138 offset:7792
	s_waitcnt lgkmcnt(3)
	v_cmp_eq_u32_e32 vcc, 47, v139
	v_mul_f32_dpp v132, -v140, v116 row_newbcast:2 row_mask:0xf bank_mask:0xf
	v_mul_f32_dpp v133, -v140, v117 row_newbcast:3 row_mask:0xf bank_mask:0xf
	v_fmac_f32_dpp v130, -v140, v118 row_newbcast:4 row_mask:0xf bank_mask:0xf
	v_mul_f32_dpp v131, -v140, v115 row_newbcast:1 row_mask:0xf bank_mask:0xf
	v_fmac_f32_dpp v132, -v140, v120 row_newbcast:6 row_mask:0xf bank_mask:0xf
	v_fmac_f32_dpp v133, -v140, v121 row_newbcast:7 row_mask:0xf bank_mask:0xf
	v_fmac_f32_dpp v130, -v140, v122 row_newbcast:8 row_mask:0xf bank_mask:0xf
	v_fmac_f32_dpp v131, -v140, v119 row_newbcast:5 row_mask:0xf bank_mask:0xf
	v_fmac_f32_dpp v132, -v140, v124 row_newbcast:10 row_mask:0xf bank_mask:0xf
	v_fmac_f32_dpp v133, -v140, v125 row_newbcast:11 row_mask:0xf bank_mask:0xf
	v_fmac_f32_dpp v130, -v140, v126 row_newbcast:12 row_mask:0xf bank_mask:0xf
	v_fmac_f32_dpp v131, -v140, v123 row_newbcast:9 row_mask:0xf bank_mask:0xf
	v_fmac_f32_dpp v132, -v140, v128 row_newbcast:14 row_mask:0xf bank_mask:0xf
	v_fmac_f32_dpp v133, -v140, v129 row_newbcast:15 row_mask:0xf bank_mask:0xf
	v_fmac_f32_dpp v131, -v140, v127 row_newbcast:13 row_mask:0xf bank_mask:0xf
	v_cndmask_b32_e64 v134, 0, 1.0, vcc
	v_add_f32_e32 v20, v130, v131
	v_add_f32_e32 v21, v132, v133
	v_add_f32_e32 v114, v20, v21
	ds_read_b32 v140, v138 offset:7648
	ds_read_b32 v141, v138 offset:7712
	s_waitcnt lgkmcnt(4)
	v_cmp_eq_u32_e32 vcc, 46, v139
	v_mul_f32_dpp v135, -v148, v115 row_newbcast:1 row_mask:0xf bank_mask:0xf
	v_mul_f32_dpp v136, -v148, v116 row_newbcast:2 row_mask:0xf bank_mask:0xf
	v_mul_f32_dpp v137, -v148, v117 row_newbcast:3 row_mask:0xf bank_mask:0xf
	v_fmac_f32_dpp v134, -v148, v114 row_newbcast:0 row_mask:0xf bank_mask:0xf
	v_fmac_f32_dpp v135, -v148, v119 row_newbcast:5 row_mask:0xf bank_mask:0xf
	v_fmac_f32_dpp v136, -v148, v120 row_newbcast:6 row_mask:0xf bank_mask:0xf
	v_fmac_f32_dpp v137, -v148, v121 row_newbcast:7 row_mask:0xf bank_mask:0xf
	v_fmac_f32_dpp v134, -v148, v118 row_newbcast:4 row_mask:0xf bank_mask:0xf
	v_fmac_f32_dpp v135, -v148, v123 row_newbcast:9 row_mask:0xf bank_mask:0xf
	v_fmac_f32_dpp v136, -v148, v124 row_newbcast:10 row_mask:0xf bank_mask:0xf
	v_fmac_f32_dpp v137, -v148, v125 row_newbcast:11 row_mask:0xf bank_mask:0xf
	v_fmac_f32_dpp v134, -v148, v122 row_newbcast:8 row_mask:0xf bank_mask:0xf
	v_fmac_f32_dpp v135, -v148, v127 row_newbcast:13 row_mask:0xf bank_mask:0xf
	v_fmac_f32_dpp v136, -v148, v128 row_newbcast:14 row_mask:0xf bank_mask:0xf
	v_fmac_f32_dpp v137, -v148, v129 row_newbcast:15 row_mask:0xf bank_mask:0xf
	v_fmac_f32_dpp v134, -v148, v126 row_newbcast:12 row_mask:0xf bank_mask:0xf
	v_cndmask_b32_e64 v130, 0, 1.0, vcc
	v_add_f32_e32 v20, v134, v135
	v_add_f32_e32 v21, v136, v137
	v_add_f32_e32 v113, v20, v21
	ds_read_b32 v148, v138 offset:7568
	ds_read_b32 v149, v138 offset:7632
	s_waitcnt lgkmcnt(4)
	v_cmp_eq_u32_e32 vcc, 45, v139
	v_fmac_f32_dpp v130, -v144, v114 row_newbcast:4 row_mask:0xf bank_mask:0xf
	v_mul_f32_dpp v131, -v144, v115 row_newbcast:5 row_mask:0xf bank_mask:0xf
	v_mul_f32_dpp v132, -v144, v116 row_newbcast:6 row_mask:0xf bank_mask:0xf
	v_mul_f32_dpp v133, -v144, v113 row_newbcast:3 row_mask:0xf bank_mask:0xf
	v_fmac_f32_dpp v130, -v144, v118 row_newbcast:8 row_mask:0xf bank_mask:0xf
	v_fmac_f32_dpp v131, -v144, v119 row_newbcast:9 row_mask:0xf bank_mask:0xf
	v_fmac_f32_dpp v132, -v144, v120 row_newbcast:10 row_mask:0xf bank_mask:0xf
	v_fmac_f32_dpp v133, -v144, v117 row_newbcast:7 row_mask:0xf bank_mask:0xf
	v_fmac_f32_dpp v130, -v144, v122 row_newbcast:12 row_mask:0xf bank_mask:0xf
	v_fmac_f32_dpp v131, -v144, v123 row_newbcast:13 row_mask:0xf bank_mask:0xf
	v_fmac_f32_dpp v132, -v144, v124 row_newbcast:14 row_mask:0xf bank_mask:0xf
	v_fmac_f32_dpp v133, -v144, v121 row_newbcast:11 row_mask:0xf bank_mask:0xf
	v_fmac_f32_dpp v130, -v145, v126 row_newbcast:0 row_mask:0xf bank_mask:0xf
	v_fmac_f32_dpp v131, -v145, v127 row_newbcast:1 row_mask:0xf bank_mask:0xf
	v_fmac_f32_dpp v132, -v145, v128 row_newbcast:2 row_mask:0xf bank_mask:0xf
	v_fmac_f32_dpp v133, -v144, v125 row_newbcast:15 row_mask:0xf bank_mask:0xf
	s_nop 1
	v_fmac_f32_dpp v133, -v145, v129 row_newbcast:3 row_mask:0xf bank_mask:0xf
	v_cndmask_b32_e64 v134, 0, 1.0, vcc
	v_add_f32_e32 v20, v130, v131
	v_add_f32_e32 v21, v132, v133
	v_add_f32_e32 v112, v20, v21
	ds_read_b32 v144, v138 offset:7488
	ds_read_b32 v145, v138 offset:7552
	s_waitcnt lgkmcnt(4)
	v_cmp_eq_u32_e32 vcc, 44, v139
	v_mul_f32_dpp v137, -v140, v113 row_newbcast:3 row_mask:0xf bank_mask:0xf
	v_fmac_f32_dpp v134, -v140, v114 row_newbcast:4 row_mask:0xf bank_mask:0xf
	v_mul_f32_dpp v135, -v140, v115 row_newbcast:5 row_mask:0xf bank_mask:0xf
	v_mul_f32_dpp v136, -v140, v112 row_newbcast:2 row_mask:0xf bank_mask:0xf
	v_fmac_f32_dpp v137, -v140, v117 row_newbcast:7 row_mask:0xf bank_mask:0xf
	v_fmac_f32_dpp v134, -v140, v118 row_newbcast:8 row_mask:0xf bank_mask:0xf
	v_fmac_f32_dpp v135, -v140, v119 row_newbcast:9 row_mask:0xf bank_mask:0xf
	v_fmac_f32_dpp v136, -v140, v116 row_newbcast:6 row_mask:0xf bank_mask:0xf
	v_fmac_f32_dpp v137, -v140, v121 row_newbcast:11 row_mask:0xf bank_mask:0xf
	v_fmac_f32_dpp v134, -v140, v122 row_newbcast:12 row_mask:0xf bank_mask:0xf
	v_fmac_f32_dpp v135, -v140, v123 row_newbcast:13 row_mask:0xf bank_mask:0xf
	v_fmac_f32_dpp v136, -v140, v120 row_newbcast:10 row_mask:0xf bank_mask:0xf
	v_fmac_f32_dpp v137, -v140, v125 row_newbcast:15 row_mask:0xf bank_mask:0xf
	v_fmac_f32_dpp v134, -v141, v126 row_newbcast:0 row_mask:0xf bank_mask:0xf
	v_fmac_f32_dpp v135, -v141, v127 row_newbcast:1 row_mask:0xf bank_mask:0xf
	v_fmac_f32_dpp v136, -v140, v124 row_newbcast:14 row_mask:0xf bank_mask:0xf
	v_fmac_f32_dpp v137, -v141, v129 row_newbcast:3 row_mask:0xf bank_mask:0xf
	s_nop 0
	v_fmac_f32_dpp v136, -v141, v128 row_newbcast:2 row_mask:0xf bank_mask:0xf
	v_cndmask_b32_e64 v130, 0, 1.0, vcc
	v_add_f32_e32 v20, v134, v135
	v_add_f32_e32 v21, v136, v137
	v_add_f32_e32 v111, v20, v21
	ds_read_b32 v140, v138 offset:7392
	ds_read_b32 v141, v138 offset:7456
	s_waitcnt lgkmcnt(4)
	v_cmp_eq_u32_e32 vcc, 43, v139
	v_mul_f32_dpp v132, -v148, v112 row_newbcast:2 row_mask:0xf bank_mask:0xf
	v_mul_f32_dpp v133, -v148, v113 row_newbcast:3 row_mask:0xf bank_mask:0xf
	v_fmac_f32_dpp v130, -v148, v114 row_newbcast:4 row_mask:0xf bank_mask:0xf
	v_mul_f32_dpp v131, -v148, v111 row_newbcast:1 row_mask:0xf bank_mask:0xf
	v_fmac_f32_dpp v132, -v148, v116 row_newbcast:6 row_mask:0xf bank_mask:0xf
	v_fmac_f32_dpp v133, -v148, v117 row_newbcast:7 row_mask:0xf bank_mask:0xf
	v_fmac_f32_dpp v130, -v148, v118 row_newbcast:8 row_mask:0xf bank_mask:0xf
	v_fmac_f32_dpp v131, -v148, v115 row_newbcast:5 row_mask:0xf bank_mask:0xf
	v_fmac_f32_dpp v132, -v148, v120 row_newbcast:10 row_mask:0xf bank_mask:0xf
	v_fmac_f32_dpp v133, -v148, v121 row_newbcast:11 row_mask:0xf bank_mask:0xf
	v_fmac_f32_dpp v130, -v148, v122 row_newbcast:12 row_mask:0xf bank_mask:0xf
	v_fmac_f32_dpp v131, -v148, v119 row_newbcast:9 row_mask:0xf bank_mask:0xf
	v_fmac_f32_dpp v132, -v148, v124 row_newbcast:14 row_mask:0xf bank_mask:0xf
	v_fmac_f32_dpp v133, -v148, v125 row_newbcast:15 row_mask:0xf bank_mask:0xf
	v_fmac_f32_dpp v130, -v149, v126 row_newbcast:0 row_mask:0xf bank_mask:0xf
	v_fmac_f32_dpp v131, -v148, v123 row_newbcast:13 row_mask:0xf bank_mask:0xf
	v_fmac_f32_dpp v132, -v149, v128 row_newbcast:2 row_mask:0xf bank_mask:0xf
	v_fmac_f32_dpp v133, -v149, v129 row_newbcast:3 row_mask:0xf bank_mask:0xf
	v_fmac_f32_dpp v131, -v149, v127 row_newbcast:1 row_mask:0xf bank_mask:0xf
	v_cndmask_b32_e64 v134, 0, 1.0, vcc
	v_add_f32_e32 v20, v130, v131
	v_add_f32_e32 v21, v132, v133
	v_add_f32_e32 v110, v20, v21
	ds_read_b32 v148, v138 offset:7296
	ds_read_b32 v149, v138 offset:7360
	s_waitcnt lgkmcnt(4)
	v_cmp_eq_u32_e32 vcc, 42, v139
	v_mul_f32_dpp v135, -v144, v111 row_newbcast:1 row_mask:0xf bank_mask:0xf
	v_mul_f32_dpp v136, -v144, v112 row_newbcast:2 row_mask:0xf bank_mask:0xf
	v_mul_f32_dpp v137, -v144, v113 row_newbcast:3 row_mask:0xf bank_mask:0xf
	v_fmac_f32_dpp v134, -v144, v110 row_newbcast:0 row_mask:0xf bank_mask:0xf
	v_fmac_f32_dpp v135, -v144, v115 row_newbcast:5 row_mask:0xf bank_mask:0xf
	v_fmac_f32_dpp v136, -v144, v116 row_newbcast:6 row_mask:0xf bank_mask:0xf
	v_fmac_f32_dpp v137, -v144, v117 row_newbcast:7 row_mask:0xf bank_mask:0xf
	v_fmac_f32_dpp v134, -v144, v114 row_newbcast:4 row_mask:0xf bank_mask:0xf
	v_fmac_f32_dpp v135, -v144, v119 row_newbcast:9 row_mask:0xf bank_mask:0xf
	v_fmac_f32_dpp v136, -v144, v120 row_newbcast:10 row_mask:0xf bank_mask:0xf
	v_fmac_f32_dpp v137, -v144, v121 row_newbcast:11 row_mask:0xf bank_mask:0xf
	v_fmac_f32_dpp v134, -v144, v118 row_newbcast:8 row_mask:0xf bank_mask:0xf
	v_fmac_f32_dpp v135, -v144, v123 row_newbcast:13 row_mask:0xf bank_mask:0xf
	v_fmac_f32_dpp v136, -v144, v124 row_newbcast:14 row_mask:0xf bank_mask:0xf
	v_fmac_f32_dpp v137, -v144, v125 row_newbcast:15 row_mask:0xf bank_mask:0xf
	v_fmac_f32_dpp v134, -v144, v122 row_newbcast:12 row_mask:0xf bank_mask:0xf
	v_fmac_f32_dpp v135, -v145, v127 row_newbcast:1 row_mask:0xf bank_mask:0xf
	v_fmac_f32_dpp v136, -v145, v128 row_newbcast:2 row_mask:0xf bank_mask:0xf
	v_fmac_f32_dpp v137, -v145, v129 row_newbcast:3 row_mask:0xf bank_mask:0xf
	v_fmac_f32_dpp v134, -v145, v126 row_newbcast:0 row_mask:0xf bank_mask:0xf
	v_cndmask_b32_e64 v130, 0, 1.0, vcc
	v_add_f32_e32 v20, v134, v135
	v_add_f32_e32 v21, v136, v137
	v_add_f32_e32 v109, v20, v21
	ds_read_b32 v144, v138 offset:7200
	ds_read_b32 v145, v138 offset:7264
	s_waitcnt lgkmcnt(4)
	v_cmp_eq_u32_e32 vcc, 41, v139
	v_fmac_f32_dpp v130, -v140, v110 row_newbcast:4 row_mask:0xf bank_mask:0xf
	v_mul_f32_dpp v131, -v140, v111 row_newbcast:5 row_mask:0xf bank_mask:0xf
	v_mul_f32_dpp v132, -v140, v112 row_newbcast:6 row_mask:0xf bank_mask:0xf
	v_mul_f32_dpp v133, -v140, v109 row_newbcast:3 row_mask:0xf bank_mask:0xf
	v_fmac_f32_dpp v130, -v140, v114 row_newbcast:8 row_mask:0xf bank_mask:0xf
	v_fmac_f32_dpp v131, -v140, v115 row_newbcast:9 row_mask:0xf bank_mask:0xf
	v_fmac_f32_dpp v132, -v140, v116 row_newbcast:10 row_mask:0xf bank_mask:0xf
	v_fmac_f32_dpp v133, -v140, v113 row_newbcast:7 row_mask:0xf bank_mask:0xf
	v_fmac_f32_dpp v130, -v140, v118 row_newbcast:12 row_mask:0xf bank_mask:0xf
	v_fmac_f32_dpp v131, -v140, v119 row_newbcast:13 row_mask:0xf bank_mask:0xf
	v_fmac_f32_dpp v132, -v140, v120 row_newbcast:14 row_mask:0xf bank_mask:0xf
	v_fmac_f32_dpp v133, -v140, v117 row_newbcast:11 row_mask:0xf bank_mask:0xf
	v_fmac_f32_dpp v130, -v141, v122 row_newbcast:0 row_mask:0xf bank_mask:0xf
	v_fmac_f32_dpp v131, -v141, v123 row_newbcast:1 row_mask:0xf bank_mask:0xf
	v_fmac_f32_dpp v132, -v141, v124 row_newbcast:2 row_mask:0xf bank_mask:0xf
	v_fmac_f32_dpp v133, -v140, v121 row_newbcast:15 row_mask:0xf bank_mask:0xf
	v_fmac_f32_dpp v130, -v141, v126 row_newbcast:4 row_mask:0xf bank_mask:0xf
	v_fmac_f32_dpp v131, -v141, v127 row_newbcast:5 row_mask:0xf bank_mask:0xf
	v_fmac_f32_dpp v132, -v141, v128 row_newbcast:6 row_mask:0xf bank_mask:0xf
	v_fmac_f32_dpp v133, -v141, v125 row_newbcast:3 row_mask:0xf bank_mask:0xf
	s_nop 1
	v_fmac_f32_dpp v133, -v141, v129 row_newbcast:7 row_mask:0xf bank_mask:0xf
	v_cndmask_b32_e64 v134, 0, 1.0, vcc
	v_add_f32_e32 v20, v130, v131
	v_add_f32_e32 v21, v132, v133
	v_add_f32_e32 v108, v20, v21
	ds_read_b32 v140, v138 offset:7104
	ds_read_b32 v141, v138 offset:7168
	s_waitcnt lgkmcnt(4)
	v_cmp_eq_u32_e32 vcc, 40, v139
	v_mul_f32_dpp v137, -v148, v109 row_newbcast:3 row_mask:0xf bank_mask:0xf
	v_fmac_f32_dpp v134, -v148, v110 row_newbcast:4 row_mask:0xf bank_mask:0xf
	v_mul_f32_dpp v135, -v148, v111 row_newbcast:5 row_mask:0xf bank_mask:0xf
	v_mul_f32_dpp v136, -v148, v108 row_newbcast:2 row_mask:0xf bank_mask:0xf
	v_fmac_f32_dpp v137, -v148, v113 row_newbcast:7 row_mask:0xf bank_mask:0xf
	v_fmac_f32_dpp v134, -v148, v114 row_newbcast:8 row_mask:0xf bank_mask:0xf
	v_fmac_f32_dpp v135, -v148, v115 row_newbcast:9 row_mask:0xf bank_mask:0xf
	v_fmac_f32_dpp v136, -v148, v112 row_newbcast:6 row_mask:0xf bank_mask:0xf
	v_fmac_f32_dpp v137, -v148, v117 row_newbcast:11 row_mask:0xf bank_mask:0xf
	v_fmac_f32_dpp v134, -v148, v118 row_newbcast:12 row_mask:0xf bank_mask:0xf
	v_fmac_f32_dpp v135, -v148, v119 row_newbcast:13 row_mask:0xf bank_mask:0xf
	v_fmac_f32_dpp v136, -v148, v116 row_newbcast:10 row_mask:0xf bank_mask:0xf
	v_fmac_f32_dpp v137, -v148, v121 row_newbcast:15 row_mask:0xf bank_mask:0xf
	v_fmac_f32_dpp v134, -v149, v122 row_newbcast:0 row_mask:0xf bank_mask:0xf
	v_fmac_f32_dpp v135, -v149, v123 row_newbcast:1 row_mask:0xf bank_mask:0xf
	v_fmac_f32_dpp v136, -v148, v120 row_newbcast:14 row_mask:0xf bank_mask:0xf
	v_fmac_f32_dpp v137, -v149, v125 row_newbcast:3 row_mask:0xf bank_mask:0xf
	v_fmac_f32_dpp v134, -v149, v126 row_newbcast:4 row_mask:0xf bank_mask:0xf
	v_fmac_f32_dpp v135, -v149, v127 row_newbcast:5 row_mask:0xf bank_mask:0xf
	s_setprio 0
	v_fmac_f32_dpp v136, -v149, v124 row_newbcast:2 row_mask:0xf bank_mask:0xf
	v_fmac_f32_dpp v137, -v149, v129 row_newbcast:7 row_mask:0xf bank_mask:0xf
	s_nop 0
	v_fmac_f32_dpp v136, -v149, v128 row_newbcast:6 row_mask:0xf bank_mask:0xf
	v_cndmask_b32_e64 v130, 0, 1.0, vcc
	v_add_f32_e32 v20, v134, v135
	v_add_f32_e32 v21, v136, v137
	v_add_f32_e32 v107, v20, v21
	ds_read_b32 v148, v138 offset:6992
	ds_read_b32 v149, v138 offset:7056
	s_waitcnt lgkmcnt(4)
	v_cmp_eq_u32_e32 vcc, 39, v139
	v_mul_f32_dpp v132, -v144, v108 row_newbcast:2 row_mask:0xf bank_mask:0xf
	v_mul_f32_dpp v133, -v144, v109 row_newbcast:3 row_mask:0xf bank_mask:0xf
	v_fmac_f32_dpp v130, -v144, v110 row_newbcast:4 row_mask:0xf bank_mask:0xf
	v_mul_f32_dpp v131, -v144, v107 row_newbcast:1 row_mask:0xf bank_mask:0xf
	v_fmac_f32_dpp v132, -v144, v112 row_newbcast:6 row_mask:0xf bank_mask:0xf
	v_fmac_f32_dpp v133, -v144, v113 row_newbcast:7 row_mask:0xf bank_mask:0xf
	v_fmac_f32_dpp v130, -v144, v114 row_newbcast:8 row_mask:0xf bank_mask:0xf
	v_fmac_f32_dpp v131, -v144, v111 row_newbcast:5 row_mask:0xf bank_mask:0xf
	v_fmac_f32_dpp v132, -v144, v116 row_newbcast:10 row_mask:0xf bank_mask:0xf
	v_fmac_f32_dpp v133, -v144, v117 row_newbcast:11 row_mask:0xf bank_mask:0xf
	v_fmac_f32_dpp v130, -v144, v118 row_newbcast:12 row_mask:0xf bank_mask:0xf
	v_fmac_f32_dpp v131, -v144, v115 row_newbcast:9 row_mask:0xf bank_mask:0xf
	v_fmac_f32_dpp v132, -v144, v120 row_newbcast:14 row_mask:0xf bank_mask:0xf
	v_fmac_f32_dpp v133, -v144, v121 row_newbcast:15 row_mask:0xf bank_mask:0xf
	v_fmac_f32_dpp v130, -v145, v122 row_newbcast:0 row_mask:0xf bank_mask:0xf
	v_fmac_f32_dpp v131, -v144, v119 row_newbcast:13 row_mask:0xf bank_mask:0xf
	v_fmac_f32_dpp v132, -v145, v124 row_newbcast:2 row_mask:0xf bank_mask:0xf
	v_fmac_f32_dpp v133, -v145, v125 row_newbcast:3 row_mask:0xf bank_mask:0xf
	v_fmac_f32_dpp v130, -v145, v126 row_newbcast:4 row_mask:0xf bank_mask:0xf
	v_fmac_f32_dpp v131, -v145, v123 row_newbcast:1 row_mask:0xf bank_mask:0xf
	v_fmac_f32_dpp v132, -v145, v128 row_newbcast:6 row_mask:0xf bank_mask:0xf
	v_fmac_f32_dpp v133, -v145, v129 row_newbcast:7 row_mask:0xf bank_mask:0xf
	v_fmac_f32_dpp v131, -v145, v127 row_newbcast:5 row_mask:0xf bank_mask:0xf
	v_cndmask_b32_e64 v134, 0, 1.0, vcc
	v_add_f32_e32 v20, v130, v131
	v_add_f32_e32 v21, v132, v133
	v_add_f32_e32 v106, v20, v21
	ds_read_b32 v144, v138 offset:6880
	ds_read_b32 v145, v138 offset:6944
	s_waitcnt lgkmcnt(4)
	v_cmp_eq_u32_e32 vcc, 38, v139
	v_mul_f32_dpp v135, -v140, v107 row_newbcast:1 row_mask:0xf bank_mask:0xf
	v_mul_f32_dpp v136, -v140, v108 row_newbcast:2 row_mask:0xf bank_mask:0xf
	v_mul_f32_dpp v137, -v140, v109 row_newbcast:3 row_mask:0xf bank_mask:0xf
	v_fmac_f32_dpp v134, -v140, v106 row_newbcast:0 row_mask:0xf bank_mask:0xf
	v_fmac_f32_dpp v135, -v140, v111 row_newbcast:5 row_mask:0xf bank_mask:0xf
	v_fmac_f32_dpp v136, -v140, v112 row_newbcast:6 row_mask:0xf bank_mask:0xf
	v_fmac_f32_dpp v137, -v140, v113 row_newbcast:7 row_mask:0xf bank_mask:0xf
	v_fmac_f32_dpp v134, -v140, v110 row_newbcast:4 row_mask:0xf bank_mask:0xf
	v_fmac_f32_dpp v135, -v140, v115 row_newbcast:9 row_mask:0xf bank_mask:0xf
	v_fmac_f32_dpp v136, -v140, v116 row_newbcast:10 row_mask:0xf bank_mask:0xf
	v_fmac_f32_dpp v137, -v140, v117 row_newbcast:11 row_mask:0xf bank_mask:0xf
	v_fmac_f32_dpp v134, -v140, v114 row_newbcast:8 row_mask:0xf bank_mask:0xf
	v_fmac_f32_dpp v135, -v140, v119 row_newbcast:13 row_mask:0xf bank_mask:0xf
	v_fmac_f32_dpp v136, -v140, v120 row_newbcast:14 row_mask:0xf bank_mask:0xf
	v_fmac_f32_dpp v137, -v140, v121 row_newbcast:15 row_mask:0xf bank_mask:0xf
	v_fmac_f32_dpp v134, -v140, v118 row_newbcast:12 row_mask:0xf bank_mask:0xf
	v_fmac_f32_dpp v135, -v141, v123 row_newbcast:1 row_mask:0xf bank_mask:0xf
	v_fmac_f32_dpp v136, -v141, v124 row_newbcast:2 row_mask:0xf bank_mask:0xf
	v_fmac_f32_dpp v137, -v141, v125 row_newbcast:3 row_mask:0xf bank_mask:0xf
	v_fmac_f32_dpp v134, -v141, v122 row_newbcast:0 row_mask:0xf bank_mask:0xf
	v_fmac_f32_dpp v135, -v141, v127 row_newbcast:5 row_mask:0xf bank_mask:0xf
	v_fmac_f32_dpp v136, -v141, v128 row_newbcast:6 row_mask:0xf bank_mask:0xf
	v_fmac_f32_dpp v137, -v141, v129 row_newbcast:7 row_mask:0xf bank_mask:0xf
	v_fmac_f32_dpp v134, -v141, v126 row_newbcast:4 row_mask:0xf bank_mask:0xf
	v_cndmask_b32_e64 v130, 0, 1.0, vcc
	v_add_f32_e32 v20, v134, v135
	v_add_f32_e32 v21, v136, v137
	v_add_f32_e32 v105, v20, v21
	ds_read_b32 v140, v138 offset:6768
	ds_read_b32 v141, v138 offset:6832
	s_waitcnt lgkmcnt(4)
	v_cmp_eq_u32_e32 vcc, 37, v139
	v_fmac_f32_dpp v130, -v148, v106 row_newbcast:4 row_mask:0xf bank_mask:0xf
	v_mul_f32_dpp v131, -v148, v107 row_newbcast:5 row_mask:0xf bank_mask:0xf
	v_mul_f32_dpp v132, -v148, v108 row_newbcast:6 row_mask:0xf bank_mask:0xf
	v_mul_f32_dpp v133, -v148, v105 row_newbcast:3 row_mask:0xf bank_mask:0xf
	v_fmac_f32_dpp v130, -v148, v110 row_newbcast:8 row_mask:0xf bank_mask:0xf
	v_fmac_f32_dpp v131, -v148, v111 row_newbcast:9 row_mask:0xf bank_mask:0xf
	v_fmac_f32_dpp v132, -v148, v112 row_newbcast:10 row_mask:0xf bank_mask:0xf
	v_fmac_f32_dpp v133, -v148, v109 row_newbcast:7 row_mask:0xf bank_mask:0xf
	v_fmac_f32_dpp v130, -v148, v114 row_newbcast:12 row_mask:0xf bank_mask:0xf
	v_fmac_f32_dpp v131, -v148, v115 row_newbcast:13 row_mask:0xf bank_mask:0xf
	v_fmac_f32_dpp v132, -v148, v116 row_newbcast:14 row_mask:0xf bank_mask:0xf
	v_fmac_f32_dpp v133, -v148, v113 row_newbcast:11 row_mask:0xf bank_mask:0xf
	v_fmac_f32_dpp v130, -v149, v118 row_newbcast:0 row_mask:0xf bank_mask:0xf
	v_fmac_f32_dpp v131, -v149, v119 row_newbcast:1 row_mask:0xf bank_mask:0xf
	v_fmac_f32_dpp v132, -v149, v120 row_newbcast:2 row_mask:0xf bank_mask:0xf
	v_fmac_f32_dpp v133, -v148, v117 row_newbcast:15 row_mask:0xf bank_mask:0xf
	v_fmac_f32_dpp v130, -v149, v122 row_newbcast:4 row_mask:0xf bank_mask:0xf
	v_fmac_f32_dpp v131, -v149, v123 row_newbcast:5 row_mask:0xf bank_mask:0xf
	v_fmac_f32_dpp v132, -v149, v124 row_newbcast:6 row_mask:0xf bank_mask:0xf
	v_fmac_f32_dpp v133, -v149, v121 row_newbcast:3 row_mask:0xf bank_mask:0xf
	v_fmac_f32_dpp v130, -v149, v126 row_newbcast:8 row_mask:0xf bank_mask:0xf
	v_fmac_f32_dpp v131, -v149, v127 row_newbcast:9 row_mask:0xf bank_mask:0xf
	v_fmac_f32_dpp v132, -v149, v128 row_newbcast:10 row_mask:0xf bank_mask:0xf
	v_fmac_f32_dpp v133, -v149, v125 row_newbcast:7 row_mask:0xf bank_mask:0xf
	s_nop 1
	v_fmac_f32_dpp v133, -v149, v129 row_newbcast:11 row_mask:0xf bank_mask:0xf
	v_cndmask_b32_e64 v134, 0, 1.0, vcc
	v_add_f32_e32 v20, v130, v131
	v_add_f32_e32 v21, v132, v133
	v_add_f32_e32 v104, v20, v21
	ds_read_b32 v148, v138 offset:6656
	ds_read_b32 v149, v138 offset:6720
	s_waitcnt lgkmcnt(4)
	v_cmp_eq_u32_e32 vcc, 36, v139
	v_mul_f32_dpp v137, -v144, v105 row_newbcast:3 row_mask:0xf bank_mask:0xf
	v_fmac_f32_dpp v134, -v144, v106 row_newbcast:4 row_mask:0xf bank_mask:0xf
	v_mul_f32_dpp v135, -v144, v107 row_newbcast:5 row_mask:0xf bank_mask:0xf
	v_mul_f32_dpp v136, -v144, v104 row_newbcast:2 row_mask:0xf bank_mask:0xf
	v_fmac_f32_dpp v137, -v144, v109 row_newbcast:7 row_mask:0xf bank_mask:0xf
	v_fmac_f32_dpp v134, -v144, v110 row_newbcast:8 row_mask:0xf bank_mask:0xf
	v_fmac_f32_dpp v135, -v144, v111 row_newbcast:9 row_mask:0xf bank_mask:0xf
	v_fmac_f32_dpp v136, -v144, v108 row_newbcast:6 row_mask:0xf bank_mask:0xf
	v_fmac_f32_dpp v137, -v144, v113 row_newbcast:11 row_mask:0xf bank_mask:0xf
	v_fmac_f32_dpp v134, -v144, v114 row_newbcast:12 row_mask:0xf bank_mask:0xf
	v_fmac_f32_dpp v135, -v144, v115 row_newbcast:13 row_mask:0xf bank_mask:0xf
	v_fmac_f32_dpp v136, -v144, v112 row_newbcast:10 row_mask:0xf bank_mask:0xf
	v_fmac_f32_dpp v137, -v144, v117 row_newbcast:15 row_mask:0xf bank_mask:0xf
	v_fmac_f32_dpp v134, -v145, v118 row_newbcast:0 row_mask:0xf bank_mask:0xf
	v_fmac_f32_dpp v135, -v145, v119 row_newbcast:1 row_mask:0xf bank_mask:0xf
	v_fmac_f32_dpp v136, -v144, v116 row_newbcast:14 row_mask:0xf bank_mask:0xf
	v_fmac_f32_dpp v137, -v145, v121 row_newbcast:3 row_mask:0xf bank_mask:0xf
	v_fmac_f32_dpp v134, -v145, v122 row_newbcast:4 row_mask:0xf bank_mask:0xf
	v_fmac_f32_dpp v135, -v145, v123 row_newbcast:5 row_mask:0xf bank_mask:0xf
	v_fmac_f32_dpp v136, -v145, v120 row_newbcast:2 row_mask:0xf bank_mask:0xf
	v_fmac_f32_dpp v137, -v145, v125 row_newbcast:7 row_mask:0xf bank_mask:0xf
	v_fmac_f32_dpp v134, -v145, v126 row_newbcast:8 row_mask:0xf bank_mask:0xf
	v_fmac_f32_dpp v135, -v145, v127 row_newbcast:9 row_mask:0xf bank_mask:0xf
	v_fmac_f32_dpp v136, -v145, v124 row_newbcast:6 row_mask:0xf bank_mask:0xf
	v_fmac_f32_dpp v137, -v145, v129 row_newbcast:11 row_mask:0xf bank_mask:0xf
	s_nop 0
	v_fmac_f32_dpp v136, -v145, v128 row_newbcast:10 row_mask:0xf bank_mask:0xf
	v_cndmask_b32_e64 v130, 0, 1.0, vcc
	v_add_f32_e32 v20, v134, v135
	v_add_f32_e32 v21, v136, v137
	v_add_f32_e32 v103, v20, v21
	ds_read_b32 v144, v138 offset:6528
	ds_read_b32 v145, v138 offset:6592
	s_waitcnt lgkmcnt(4)
	v_cmp_eq_u32_e32 vcc, 35, v139
	v_mul_f32_dpp v132, -v140, v104 row_newbcast:2 row_mask:0xf bank_mask:0xf
	v_mul_f32_dpp v133, -v140, v105 row_newbcast:3 row_mask:0xf bank_mask:0xf
	v_fmac_f32_dpp v130, -v140, v106 row_newbcast:4 row_mask:0xf bank_mask:0xf
	v_mul_f32_dpp v131, -v140, v103 row_newbcast:1 row_mask:0xf bank_mask:0xf
	v_fmac_f32_dpp v132, -v140, v108 row_newbcast:6 row_mask:0xf bank_mask:0xf
	v_fmac_f32_dpp v133, -v140, v109 row_newbcast:7 row_mask:0xf bank_mask:0xf
	v_fmac_f32_dpp v130, -v140, v110 row_newbcast:8 row_mask:0xf bank_mask:0xf
	v_fmac_f32_dpp v131, -v140, v107 row_newbcast:5 row_mask:0xf bank_mask:0xf
	v_fmac_f32_dpp v132, -v140, v112 row_newbcast:10 row_mask:0xf bank_mask:0xf
	v_fmac_f32_dpp v133, -v140, v113 row_newbcast:11 row_mask:0xf bank_mask:0xf
	v_fmac_f32_dpp v130, -v140, v114 row_newbcast:12 row_mask:0xf bank_mask:0xf
	v_fmac_f32_dpp v131, -v140, v111 row_newbcast:9 row_mask:0xf bank_mask:0xf
	v_fmac_f32_dpp v132, -v140, v116 row_newbcast:14 row_mask:0xf bank_mask:0xf
	v_fmac_f32_dpp v133, -v140, v117 row_newbcast:15 row_mask:0xf bank_mask:0xf
	v_fmac_f32_dpp v130, -v141, v118 row_newbcast:0 row_mask:0xf bank_mask:0xf
	v_fmac_f32_dpp v131, -v140, v115 row_newbcast:13 row_mask:0xf bank_mask:0xf
	v_fmac_f32_dpp v132, -v141, v120 row_newbcast:2 row_mask:0xf bank_mask:0xf
	v_fmac_f32_dpp v133, -v141, v121 row_newbcast:3 row_mask:0xf bank_mask:0xf
	v_fmac_f32_dpp v130, -v141, v122 row_newbcast:4 row_mask:0xf bank_mask:0xf
	v_fmac_f32_dpp v131, -v141, v119 row_newbcast:1 row_mask:0xf bank_mask:0xf
	v_fmac_f32_dpp v132, -v141, v124 row_newbcast:6 row_mask:0xf bank_mask:0xf
	v_fmac_f32_dpp v133, -v141, v125 row_newbcast:7 row_mask:0xf bank_mask:0xf
	v_fmac_f32_dpp v130, -v141, v126 row_newbcast:8 row_mask:0xf bank_mask:0xf
	v_fmac_f32_dpp v131, -v141, v123 row_newbcast:5 row_mask:0xf bank_mask:0xf
	v_fmac_f32_dpp v132, -v141, v128 row_newbcast:10 row_mask:0xf bank_mask:0xf
	v_fmac_f32_dpp v133, -v141, v129 row_newbcast:11 row_mask:0xf bank_mask:0xf
	v_fmac_f32_dpp v131, -v141, v127 row_newbcast:9 row_mask:0xf bank_mask:0xf
	v_cndmask_b32_e64 v134, 0, 1.0, vcc
	v_add_f32_e32 v20, v130, v131
	v_add_f32_e32 v21, v132, v133
	v_add_f32_e32 v102, v20, v21
	ds_read_b32 v140, v138 offset:6400
	ds_read_b32 v141, v138 offset:6464
	s_waitcnt lgkmcnt(4)
	v_cmp_eq_u32_e32 vcc, 34, v139
	v_mul_f32_dpp v135, -v148, v103 row_newbcast:1 row_mask:0xf bank_mask:0xf
	v_mul_f32_dpp v136, -v148, v104 row_newbcast:2 row_mask:0xf bank_mask:0xf
	v_mul_f32_dpp v137, -v148, v105 row_newbcast:3 row_mask:0xf bank_mask:0xf
	v_fmac_f32_dpp v134, -v148, v102 row_newbcast:0 row_mask:0xf bank_mask:0xf
	v_fmac_f32_dpp v135, -v148, v107 row_newbcast:5 row_mask:0xf bank_mask:0xf
	v_fmac_f32_dpp v136, -v148, v108 row_newbcast:6 row_mask:0xf bank_mask:0xf
	v_fmac_f32_dpp v137, -v148, v109 row_newbcast:7 row_mask:0xf bank_mask:0xf
	v_fmac_f32_dpp v134, -v148, v106 row_newbcast:4 row_mask:0xf bank_mask:0xf
	v_fmac_f32_dpp v135, -v148, v111 row_newbcast:9 row_mask:0xf bank_mask:0xf
	v_fmac_f32_dpp v136, -v148, v112 row_newbcast:10 row_mask:0xf bank_mask:0xf
	v_fmac_f32_dpp v137, -v148, v113 row_newbcast:11 row_mask:0xf bank_mask:0xf
	v_fmac_f32_dpp v134, -v148, v110 row_newbcast:8 row_mask:0xf bank_mask:0xf
	v_fmac_f32_dpp v135, -v148, v115 row_newbcast:13 row_mask:0xf bank_mask:0xf
	v_fmac_f32_dpp v136, -v148, v116 row_newbcast:14 row_mask:0xf bank_mask:0xf
	v_fmac_f32_dpp v137, -v148, v117 row_newbcast:15 row_mask:0xf bank_mask:0xf
	v_fmac_f32_dpp v134, -v148, v114 row_newbcast:12 row_mask:0xf bank_mask:0xf
	v_fmac_f32_dpp v135, -v149, v119 row_newbcast:1 row_mask:0xf bank_mask:0xf
	v_fmac_f32_dpp v136, -v149, v120 row_newbcast:2 row_mask:0xf bank_mask:0xf
	v_fmac_f32_dpp v137, -v149, v121 row_newbcast:3 row_mask:0xf bank_mask:0xf
	v_fmac_f32_dpp v134, -v149, v118 row_newbcast:0 row_mask:0xf bank_mask:0xf
	v_fmac_f32_dpp v135, -v149, v123 row_newbcast:5 row_mask:0xf bank_mask:0xf
	v_fmac_f32_dpp v136, -v149, v124 row_newbcast:6 row_mask:0xf bank_mask:0xf
	v_fmac_f32_dpp v137, -v149, v125 row_newbcast:7 row_mask:0xf bank_mask:0xf
	v_fmac_f32_dpp v134, -v149, v122 row_newbcast:4 row_mask:0xf bank_mask:0xf
	v_fmac_f32_dpp v135, -v149, v127 row_newbcast:9 row_mask:0xf bank_mask:0xf
	v_fmac_f32_dpp v136, -v149, v128 row_newbcast:10 row_mask:0xf bank_mask:0xf
	v_fmac_f32_dpp v137, -v149, v129 row_newbcast:11 row_mask:0xf bank_mask:0xf
	v_fmac_f32_dpp v134, -v149, v126 row_newbcast:8 row_mask:0xf bank_mask:0xf
	v_cndmask_b32_e64 v130, 0, 1.0, vcc
	v_add_f32_e32 v20, v134, v135
	v_add_f32_e32 v21, v136, v137
	v_add_f32_e32 v101, v20, v21
	ds_read_b32 v148, v138 offset:6272
	ds_read_b32 v149, v138 offset:6336
	s_waitcnt lgkmcnt(4)
	v_cmp_eq_u32_e32 vcc, 33, v139
	v_fmac_f32_dpp v130, -v144, v102 row_newbcast:4 row_mask:0xf bank_mask:0xf
	v_mul_f32_dpp v131, -v144, v103 row_newbcast:5 row_mask:0xf bank_mask:0xf
	v_mul_f32_dpp v132, -v144, v104 row_newbcast:6 row_mask:0xf bank_mask:0xf
	v_mul_f32_dpp v133, -v144, v101 row_newbcast:3 row_mask:0xf bank_mask:0xf
	v_fmac_f32_dpp v130, -v144, v106 row_newbcast:8 row_mask:0xf bank_mask:0xf
	v_fmac_f32_dpp v131, -v144, v107 row_newbcast:9 row_mask:0xf bank_mask:0xf
	v_fmac_f32_dpp v132, -v144, v108 row_newbcast:10 row_mask:0xf bank_mask:0xf
	v_fmac_f32_dpp v133, -v144, v105 row_newbcast:7 row_mask:0xf bank_mask:0xf
	v_fmac_f32_dpp v130, -v144, v110 row_newbcast:12 row_mask:0xf bank_mask:0xf
	v_fmac_f32_dpp v131, -v144, v111 row_newbcast:13 row_mask:0xf bank_mask:0xf
	v_fmac_f32_dpp v132, -v144, v112 row_newbcast:14 row_mask:0xf bank_mask:0xf
	v_fmac_f32_dpp v133, -v144, v109 row_newbcast:11 row_mask:0xf bank_mask:0xf
	v_fmac_f32_dpp v130, -v145, v114 row_newbcast:0 row_mask:0xf bank_mask:0xf
	v_fmac_f32_dpp v131, -v145, v115 row_newbcast:1 row_mask:0xf bank_mask:0xf
	v_fmac_f32_dpp v132, -v145, v116 row_newbcast:2 row_mask:0xf bank_mask:0xf
	v_fmac_f32_dpp v133, -v144, v113 row_newbcast:15 row_mask:0xf bank_mask:0xf
	v_fmac_f32_dpp v130, -v145, v118 row_newbcast:4 row_mask:0xf bank_mask:0xf
	v_fmac_f32_dpp v131, -v145, v119 row_newbcast:5 row_mask:0xf bank_mask:0xf
	v_fmac_f32_dpp v132, -v145, v120 row_newbcast:6 row_mask:0xf bank_mask:0xf
	v_fmac_f32_dpp v133, -v145, v117 row_newbcast:3 row_mask:0xf bank_mask:0xf
	v_fmac_f32_dpp v130, -v145, v122 row_newbcast:8 row_mask:0xf bank_mask:0xf
	v_fmac_f32_dpp v131, -v145, v123 row_newbcast:9 row_mask:0xf bank_mask:0xf
	v_fmac_f32_dpp v132, -v145, v124 row_newbcast:10 row_mask:0xf bank_mask:0xf
	v_fmac_f32_dpp v133, -v145, v121 row_newbcast:7 row_mask:0xf bank_mask:0xf
	v_fmac_f32_dpp v130, -v145, v126 row_newbcast:12 row_mask:0xf bank_mask:0xf
	v_fmac_f32_dpp v131, -v145, v127 row_newbcast:13 row_mask:0xf bank_mask:0xf
	v_fmac_f32_dpp v132, -v145, v128 row_newbcast:14 row_mask:0xf bank_mask:0xf
	v_fmac_f32_dpp v133, -v145, v125 row_newbcast:11 row_mask:0xf bank_mask:0xf
	s_nop 1
	v_fmac_f32_dpp v133, -v145, v129 row_newbcast:15 row_mask:0xf bank_mask:0xf
	v_cndmask_b32_e64 v134, 0, 1.0, vcc
	v_add_f32_e32 v20, v130, v131
	v_add_f32_e32 v21, v132, v133
	v_add_f32_e32 v100, v20, v21
	s_waitcnt lgkmcnt(2)
	v_cmp_eq_u32_e32 vcc, 32, v139
	v_mul_f32_dpp v137, -v140, v101 row_newbcast:3 row_mask:0xf bank_mask:0xf
	v_fmac_f32_dpp v134, -v140, v102 row_newbcast:4 row_mask:0xf bank_mask:0xf
	v_mul_f32_dpp v135, -v140, v103 row_newbcast:5 row_mask:0xf bank_mask:0xf
	v_mul_f32_dpp v136, -v140, v100 row_newbcast:2 row_mask:0xf bank_mask:0xf
	v_fmac_f32_dpp v137, -v140, v105 row_newbcast:7 row_mask:0xf bank_mask:0xf
	v_fmac_f32_dpp v134, -v140, v106 row_newbcast:8 row_mask:0xf bank_mask:0xf
	v_fmac_f32_dpp v135, -v140, v107 row_newbcast:9 row_mask:0xf bank_mask:0xf
	v_fmac_f32_dpp v136, -v140, v104 row_newbcast:6 row_mask:0xf bank_mask:0xf
	v_fmac_f32_dpp v137, -v140, v109 row_newbcast:11 row_mask:0xf bank_mask:0xf
	v_fmac_f32_dpp v134, -v140, v110 row_newbcast:12 row_mask:0xf bank_mask:0xf
	v_fmac_f32_dpp v135, -v140, v111 row_newbcast:13 row_mask:0xf bank_mask:0xf
	v_fmac_f32_dpp v136, -v140, v108 row_newbcast:10 row_mask:0xf bank_mask:0xf
	v_fmac_f32_dpp v137, -v140, v113 row_newbcast:15 row_mask:0xf bank_mask:0xf
	v_fmac_f32_dpp v134, -v141, v114 row_newbcast:0 row_mask:0xf bank_mask:0xf
	v_fmac_f32_dpp v135, -v141, v115 row_newbcast:1 row_mask:0xf bank_mask:0xf
	v_fmac_f32_dpp v136, -v140, v112 row_newbcast:14 row_mask:0xf bank_mask:0xf
	v_fmac_f32_dpp v137, -v141, v117 row_newbcast:3 row_mask:0xf bank_mask:0xf
	v_fmac_f32_dpp v134, -v141, v118 row_newbcast:4 row_mask:0xf bank_mask:0xf
	v_fmac_f32_dpp v135, -v141, v119 row_newbcast:5 row_mask:0xf bank_mask:0xf
	v_fmac_f32_dpp v136, -v141, v116 row_newbcast:2 row_mask:0xf bank_mask:0xf
	v_fmac_f32_dpp v137, -v141, v121 row_newbcast:7 row_mask:0xf bank_mask:0xf
	v_fmac_f32_dpp v134, -v141, v122 row_newbcast:8 row_mask:0xf bank_mask:0xf
	v_fmac_f32_dpp v135, -v141, v123 row_newbcast:9 row_mask:0xf bank_mask:0xf
	v_fmac_f32_dpp v136, -v141, v120 row_newbcast:6 row_mask:0xf bank_mask:0xf
	v_fmac_f32_dpp v137, -v141, v125 row_newbcast:11 row_mask:0xf bank_mask:0xf
	v_fmac_f32_dpp v134, -v141, v126 row_newbcast:12 row_mask:0xf bank_mask:0xf
	v_fmac_f32_dpp v135, -v141, v127 row_newbcast:13 row_mask:0xf bank_mask:0xf
	v_fmac_f32_dpp v136, -v141, v124 row_newbcast:10 row_mask:0xf bank_mask:0xf
	v_fmac_f32_dpp v137, -v141, v129 row_newbcast:15 row_mask:0xf bank_mask:0xf
	s_nop 0
	v_fmac_f32_dpp v136, -v141, v128 row_newbcast:14 row_mask:0xf bank_mask:0xf
	v_cndmask_b32_e64 v130, 0, 1.0, vcc
	v_add_f32_e32 v20, v134, v135
	v_add_f32_e32 v21, v136, v137
	v_add_f32_e32 v99, v20, v21
	s_waitcnt lgkmcnt(0)
	v_mul_f32_dpp v132, -v148, v100 row_newbcast:2 row_mask:0xf bank_mask:0xf
	v_mul_f32_dpp v133, -v148, v101 row_newbcast:3 row_mask:0xf bank_mask:0xf
	v_fmac_f32_dpp v130, -v148, v102 row_newbcast:4 row_mask:0xf bank_mask:0xf
	v_mul_f32_dpp v131, -v148, v99 row_newbcast:1 row_mask:0xf bank_mask:0xf
	v_fmac_f32_dpp v132, -v148, v104 row_newbcast:6 row_mask:0xf bank_mask:0xf
	v_fmac_f32_dpp v133, -v148, v105 row_newbcast:7 row_mask:0xf bank_mask:0xf
	v_fmac_f32_dpp v130, -v148, v106 row_newbcast:8 row_mask:0xf bank_mask:0xf
	v_fmac_f32_dpp v131, -v148, v103 row_newbcast:5 row_mask:0xf bank_mask:0xf
	v_fmac_f32_dpp v132, -v148, v108 row_newbcast:10 row_mask:0xf bank_mask:0xf
	v_fmac_f32_dpp v133, -v148, v109 row_newbcast:11 row_mask:0xf bank_mask:0xf
	v_fmac_f32_dpp v130, -v148, v110 row_newbcast:12 row_mask:0xf bank_mask:0xf
	v_fmac_f32_dpp v131, -v148, v107 row_newbcast:9 row_mask:0xf bank_mask:0xf
	v_fmac_f32_dpp v132, -v148, v112 row_newbcast:14 row_mask:0xf bank_mask:0xf
	v_fmac_f32_dpp v133, -v148, v113 row_newbcast:15 row_mask:0xf bank_mask:0xf
	v_fmac_f32_dpp v130, -v149, v114 row_newbcast:0 row_mask:0xf bank_mask:0xf
	v_fmac_f32_dpp v131, -v148, v111 row_newbcast:13 row_mask:0xf bank_mask:0xf
	v_fmac_f32_dpp v132, -v149, v116 row_newbcast:2 row_mask:0xf bank_mask:0xf
	v_fmac_f32_dpp v133, -v149, v117 row_newbcast:3 row_mask:0xf bank_mask:0xf
	v_fmac_f32_dpp v130, -v149, v118 row_newbcast:4 row_mask:0xf bank_mask:0xf
	v_fmac_f32_dpp v131, -v149, v115 row_newbcast:1 row_mask:0xf bank_mask:0xf
	v_fmac_f32_dpp v132, -v149, v120 row_newbcast:6 row_mask:0xf bank_mask:0xf
	v_fmac_f32_dpp v133, -v149, v121 row_newbcast:7 row_mask:0xf bank_mask:0xf
	v_fmac_f32_dpp v130, -v149, v122 row_newbcast:8 row_mask:0xf bank_mask:0xf
	v_fmac_f32_dpp v131, -v149, v119 row_newbcast:5 row_mask:0xf bank_mask:0xf
	v_fmac_f32_dpp v132, -v149, v124 row_newbcast:10 row_mask:0xf bank_mask:0xf
	v_fmac_f32_dpp v133, -v149, v125 row_newbcast:11 row_mask:0xf bank_mask:0xf
	v_fmac_f32_dpp v130, -v149, v126 row_newbcast:12 row_mask:0xf bank_mask:0xf
	v_fmac_f32_dpp v131, -v149, v123 row_newbcast:9 row_mask:0xf bank_mask:0xf
	v_fmac_f32_dpp v132, -v149, v128 row_newbcast:14 row_mask:0xf bank_mask:0xf
	v_fmac_f32_dpp v133, -v149, v129 row_newbcast:15 row_mask:0xf bank_mask:0xf
	v_fmac_f32_dpp v131, -v149, v127 row_newbcast:13 row_mask:0xf bank_mask:0xf
	v_add_f32_e32 v20, v130, v131
	v_add_f32_e32 v21, v132, v133
	v_add_f32_e32 v98, v20, v21
	v_cndmask_b32_e64 v176, -v98, -v99, s[2:3]
	v_cndmask_b32_e64 v177, -v100, -v101, s[2:3]
	v_cndmask_b32_e64 v178, -v102, -v103, s[2:3]
	v_cndmask_b32_e64 v179, -v104, -v105, s[2:3]
	v_cndmask_b32_e64 v180, -v106, -v107, s[2:3]
	v_cndmask_b32_e64 v181, -v108, -v109, s[2:3]
	v_cndmask_b32_e64 v182, -v110, -v111, s[2:3]
	v_cndmask_b32_e64 v183, -v112, -v113, s[2:3]
	v_cndmask_b32_e64 v242, -v114, -v115, s[2:3]
	v_cndmask_b32_e64 v243, -v116, -v117, s[2:3]
	v_cndmask_b32_e64 v244, -v118, -v119, s[2:3]
	v_cndmask_b32_e64 v245, -v120, -v121, s[2:3]
	v_cndmask_b32_e64 v246, -v122, -v123, s[2:3]
	v_cndmask_b32_e64 v247, -v124, -v125, s[2:3]
	v_cndmask_b32_e64 v156, -v126, -v127, s[2:3]
	v_cndmask_b32_e64 v157, -v128, -v129, s[2:3]
	s_waitcnt lgkmcnt(0)
	s_nop 1
	v_mfma_f32_32x32x2_f32 v[2:17], v226, v176, 0
	v_mfma_f32_32x32x2_f32 v[2:17], v227, v177, v[2:17]
	v_mfma_f32_32x32x2_f32 v[2:17], v228, v178, v[2:17]
	v_mfma_f32_32x32x2_f32 v[2:17], v229, v179, v[2:17]
	v_mfma_f32_32x32x2_f32 v[2:17], v230, v180, v[2:17]
	v_mfma_f32_32x32x2_f32 v[2:17], v231, v181, v[2:17]
	v_mfma_f32_32x32x2_f32 v[2:17], v232, v182, v[2:17]
	v_mfma_f32_32x32x2_f32 v[2:17], v233, v183, v[2:17]
	v_mfma_f32_32x32x2_f32 v[2:17], v234, v242, v[2:17]
	v_mfma_f32_32x32x2_f32 v[2:17], v235, v243, v[2:17]
	v_mfma_f32_32x32x2_f32 v[2:17], v236, v244, v[2:17]
	v_mfma_f32_32x32x2_f32 v[2:17], v237, v245, v[2:17]
	v_mfma_f32_32x32x2_f32 v[2:17], v238, v246, v[2:17]
	v_mfma_f32_32x32x2_f32 v[2:17], v239, v247, v[2:17]
	v_mfma_f32_32x32x2_f32 v[2:17], v240, v156, v[2:17]
	v_mfma_f32_32x32x2_f32 v[2:17], v241, v157, v[2:17]
	v_cmp_eq_u32_e32 vcc, 0, v153
	s_nop 1
	v_cndmask_b32_e64 v160, 0, 1.0, vcc
	v_cmp_eq_u32_e32 vcc, 1, v153
	s_nop 1
	v_cndmask_b32_e64 v161, 0, 1.0, vcc
	v_cmp_eq_u32_e32 vcc, 2, v153
	s_nop 1
	v_cndmask_b32_e64 v162, 0, 1.0, vcc
	v_cmp_eq_u32_e32 vcc, 3, v153
	s_nop 1
	v_cndmask_b32_e64 v163, 0, 1.0, vcc
	v_cmp_eq_u32_e32 vcc, 8, v153
	s_nop 1
	v_cndmask_b32_e64 v164, 0, 1.0, vcc
	v_cmp_eq_u32_e32 vcc, 9, v153
	s_nop 1
	v_cndmask_b32_e64 v165, 0, 1.0, vcc
	v_cmp_eq_u32_e32 vcc, 10, v153
	s_nop 1
	v_cndmask_b32_e64 v166, 0, 1.0, vcc
	v_cmp_eq_u32_e32 vcc, 11, v153
	s_nop 1
	v_cndmask_b32_e64 v167, 0, 1.0, vcc
	v_cmp_eq_u32_e32 vcc, 16, v153
	s_nop 1
	v_cndmask_b32_e64 v168, 0, 1.0, vcc
	v_cmp_eq_u32_e32 vcc, 17, v153
	s_nop 1
	v_cndmask_b32_e64 v169, 0, 1.0, vcc
	v_cmp_eq_u32_e32 vcc, 18, v153
	s_nop 1
	v_cndmask_b32_e64 v170, 0, 1.0, vcc
	v_cmp_eq_u32_e32 vcc, 19, v153
	s_nop 1
	v_cndmask_b32_e64 v171, 0, 1.0, vcc
	v_cmp_eq_u32_e32 vcc, 24, v153
	s_nop 1
	v_cndmask_b32_e64 v172, 0, 1.0, vcc
	v_cmp_eq_u32_e32 vcc, 25, v153
	s_nop 1
	v_cndmask_b32_e64 v173, 0, 1.0, vcc
	v_cmp_eq_u32_e32 vcc, 26, v153
	s_nop 1
	v_cndmask_b32_e64 v174, 0, 1.0, vcc
	v_cmp_eq_u32_e32 vcc, 27, v153
	s_nop 1
	v_cndmask_b32_e64 v175, 0, 1.0, vcc
	v_permlane32_swap_b32_e32 v160, v2
	v_permlane32_swap_b32_e32 v161, v3
	v_permlane32_swap_b32_e32 v162, v4
	v_permlane32_swap_b32_e32 v163, v5
	v_permlane32_swap_b32_e32 v164, v6
	v_permlane32_swap_b32_e32 v165, v7
	v_permlane32_swap_b32_e32 v166, v8
	v_permlane32_swap_b32_e32 v167, v9
	v_permlane32_swap_b32_e32 v168, v10
	v_permlane32_swap_b32_e32 v169, v11
	v_permlane32_swap_b32_e32 v170, v12
	v_permlane32_swap_b32_e32 v171, v13
	v_permlane32_swap_b32_e32 v172, v14
	v_permlane32_swap_b32_e32 v173, v15
	v_permlane32_swap_b32_e32 v174, v16
	v_permlane32_swap_b32_e32 v175, v17
	ds_read_b32 v140, v138 offset:6000
	ds_read_b32 v148, v138 offset:5856
	s_waitcnt lgkmcnt(2)
	v_mov_b32_e32 v97, v17
	ds_read_b32 v144, v138 offset:5712
	s_waitcnt lgkmcnt(2)
	v_mul_f32_dpp v133, -v140, v97 row_newbcast:3 row_mask:0xf bank_mask:0xf
	v_add_f32_e32 v96, v16, v133
	ds_read_b32 v140, v138 offset:5568
	s_waitcnt lgkmcnt(2)
	v_mul_f32_dpp v137, -v148, v97 row_newbcast:3 row_mask:0xf bank_mask:0xf
	v_mul_f32_dpp v136, -v148, v96 row_newbcast:2 row_mask:0xf bank_mask:0xf
	v_add_f32_e32 v21, v136, v137
	v_add_f32_e32 v95, v15, v21
	ds_read_b32 v148, v138 offset:5408
	s_waitcnt lgkmcnt(2)
	v_mul_f32_dpp v132, -v144, v96 row_newbcast:2 row_mask:0xf bank_mask:0xf
	v_mul_f32_dpp v133, -v144, v97 row_newbcast:3 row_mask:0xf bank_mask:0xf
	v_mul_f32_dpp v131, -v144, v95 row_newbcast:1 row_mask:0xf bank_mask:0xf
	v_add_f32_e32 v20, v14, v131
	v_add_f32_e32 v21, v132, v133
	v_add_f32_e32 v94, v20, v21
	ds_read_b32 v144, v138 offset:5248
	s_waitcnt lgkmcnt(2)
	v_mul_f32_dpp v135, -v140, v95 row_newbcast:1 row_mask:0xf bank_mask:0xf
	v_mul_f32_dpp v136, -v140, v96 row_newbcast:2 row_mask:0xf bank_mask:0xf
	v_mul_f32_dpp v137, -v140, v97 row_newbcast:3 row_mask:0xf bank_mask:0xf
	v_fmac_f32_dpp v175, -v140, v94 row_newbcast:0 row_mask:0xf bank_mask:0xf
	v_add_f32_e32 v20, v175, v135
	v_add_f32_e32 v21, v136, v137
	v_add_f32_e32 v93, v20, v21
	ds_read_b32 v140, v138 offset:5088
	s_waitcnt lgkmcnt(2)
	v_fmac_f32_dpp v174, -v148, v94 row_newbcast:4 row_mask:0xf bank_mask:0xf
	v_mul_f32_dpp v131, -v148, v95 row_newbcast:5 row_mask:0xf bank_mask:0xf
	v_mul_f32_dpp v132, -v148, v96 row_newbcast:6 row_mask:0xf bank_mask:0xf
	v_mul_f32_dpp v133, -v148, v93 row_newbcast:3 row_mask:0xf bank_mask:0xf
	s_nop 1
	v_fmac_f32_dpp v133, -v148, v97 row_newbcast:7 row_mask:0xf bank_mask:0xf
	v_add_f32_e32 v20, v174, v131
	v_add_f32_e32 v21, v132, v133
	v_add_f32_e32 v92, v20, v21
	ds_read_b32 v148, v138 offset:4928
	s_waitcnt lgkmcnt(2)
	v_mul_f32_dpp v137, -v144, v93 row_newbcast:3 row_mask:0xf bank_mask:0xf
	v_fmac_f32_dpp v173, -v144, v94 row_newbcast:4 row_mask:0xf bank_mask:0xf
	v_mul_f32_dpp v135, -v144, v95 row_newbcast:5 row_mask:0xf bank_mask:0xf
	v_mul_f32_dpp v136, -v144, v92 row_newbcast:2 row_mask:0xf bank_mask:0xf
	v_fmac_f32_dpp v137, -v144, v97 row_newbcast:7 row_mask:0xf bank_mask:0xf
	s_nop 0
	v_fmac_f32_dpp v136, -v144, v96 row_newbcast:6 row_mask:0xf bank_mask:0xf
	v_add_f32_e32 v20, v173, v135
	v_add_f32_e32 v21, v136, v137
	v_add_f32_e32 v91, v20, v21
	ds_read_b32 v144, v138 offset:4752
	s_waitcnt lgkmcnt(2)
	v_mul_f32_dpp v132, -v140, v92 row_newbcast:2 row_mask:0xf bank_mask:0xf
	v_mul_f32_dpp v133, -v140, v93 row_newbcast:3 row_mask:0xf bank_mask:0xf
	v_fmac_f32_dpp v172, -v140, v94 row_newbcast:4 row_mask:0xf bank_mask:0xf
	v_mul_f32_dpp v131, -v140, v91 row_newbcast:1 row_mask:0xf bank_mask:0xf
	v_fmac_f32_dpp v132, -v140, v96 row_newbcast:6 row_mask:0xf bank_mask:0xf
	v_fmac_f32_dpp v133, -v140, v97 row_newbcast:7 row_mask:0xf bank_mask:0xf
	v_fmac_f32_dpp v131, -v140, v95 row_newbcast:5 row_mask:0xf bank_mask:0xf
	v_add_f32_e32 v20, v172, v131
	v_add_f32_e32 v21, v132, v133
	v_add_f32_e32 v90, v20, v21
	ds_read_b32 v140, v138 offset:4576
	s_waitcnt lgkmcnt(2)
	v_mul_f32_dpp v135, -v148, v91 row_newbcast:1 row_mask:0xf bank_mask:0xf
	v_mul_f32_dpp v136, -v148, v92 row_newbcast:2 row_mask:0xf bank_mask:0xf
	v_mul_f32_dpp v137, -v148, v93 row_newbcast:3 row_mask:0xf bank_mask:0xf
	v_fmac_f32_dpp v13, -v148, v90 row_newbcast:0 row_mask:0xf bank_mask:0xf
	v_fmac_f32_dpp v135, -v148, v95 row_newbcast:5 row_mask:0xf bank_mask:0xf
	v_fmac_f32_dpp v136, -v148, v96 row_newbcast:6 row_mask:0xf bank_mask:0xf
	v_fmac_f32_dpp v137, -v148, v97 row_newbcast:7 row_mask:0xf bank_mask:0xf
	v_fmac_f32_dpp v13, -v148, v94 row_newbcast:4 row_mask:0xf bank_mask:0xf
	v_add_f32_e32 v20, v13, v135
	v_add_f32_e32 v21, v136, v137
	v_add_f32_e32 v89, v20, v21
	ds_read_b32 v148, v138 offset:4400
	s_waitcnt lgkmcnt(2)
	v_fmac_f32_dpp v12, -v144, v90 row_newbcast:4 row_mask:0xf bank_mask:0xf
	v_mul_f32_dpp v131, -v144, v91 row_newbcast:5 row_mask:0xf bank_mask:0xf
	v_mul_f32_dpp v132, -v144, v92 row_newbcast:6 row_mask:0xf bank_mask:0xf
	v_mul_f32_dpp v133, -v144, v89 row_newbcast:3 row_mask:0xf bank_mask:0xf
	v_fmac_f32_dpp v12, -v144, v94 row_newbcast:8 row_mask:0xf bank_mask:0xf
	v_fmac_f32_dpp v131, -v144, v95 row_newbcast:9 row_mask:0xf bank_mask:0xf
	v_fmac_f32_dpp v132, -v144, v96 row_newbcast:10 row_mask:0xf bank_mask:0xf
	v_fmac_f32_dpp v133, -v144, v93 row_newbcast:7 row_mask:0xf bank_mask:0xf
	s_nop 1
	v_fmac_f32_dpp v133, -v144, v97 row_newbcast:11 row_mask:0xf bank_mask:0xf
	v_add_f32_e32 v20, v12, v131
	v_add_f32_e32 v21, v132, v133
	v_add_f32_e32 v88, v20, v21
	ds_read_b32 v144, v138 offset:4224
	s_waitcnt lgkmcnt(2)
	v_mul_f32_dpp v137, -v140, v89 row_newbcast:3 row_mask:0xf bank_mask:0xf
	v_fmac_f32_dpp v11, -v140, v90 row_newbcast:4 row_mask:0xf bank_mask:0xf
	v_mul_f32_dpp v135, -v140, v91 row_newbcast:5 row_mask:0xf bank_mask:0xf
	v_mul_f32_dpp v136, -v140, v88 row_newbcast:2 row_mask:0xf bank_mask:0xf
	v_fmac_f32_dpp v137, -v140, v93 row_newbcast:7 row_mask:0xf bank_mask:0xf
	v_fmac_f32_dpp v11, -v140, v94 row_newbcast:8 row_mask:0xf bank_mask:0xf
	v_fmac_f32_dpp v135, -v140, v95 row_newbcast:9 row_mask:0xf bank_mask:0xf
	v_fmac_f32_dpp v136, -v140, v92 row_newbcast:6 row_mask:0xf bank_mask:0xf
	v_fmac_f32_dpp v137, -v140, v97 row_newbcast:11 row_mask:0xf bank_mask:0xf
	s_nop 0
	v_fmac_f32_dpp v136, -v140, v96 row_newbcast:10 row_mask:0xf bank_mask:0xf
	v_add_f32_e32 v20, v11, v135
	v_add_f32_e32 v21, v136, v137
	v_add_f32_e32 v87, v20, v21
	ds_read_b32 v140, v138 offset:4032
	s_waitcnt lgkmcnt(2)
	v_mul_f32_dpp v132, -v148, v88 row_newbcast:2 row_mask:0xf bank_mask:0xf
	v_mul_f32_dpp v133, -v148, v89 row_newbcast:3 row_mask:0xf bank_mask:0xf
	v_fmac_f32_dpp v10, -v148, v90 row_newbcast:4 row_mask:0xf bank_mask:0xf
	v_mul_f32_dpp v131, -v148, v87 row_newbcast:1 row_mask:0xf bank_mask:0xf
	v_fmac_f32_dpp v132, -v148, v92 row_newbcast:6 row_mask:0xf bank_mask:0xf
	v_fmac_f32_dpp v133, -v148, v93 row_newbcast:7 row_mask:0xf bank_mask:0xf
	v_fmac_f32_dpp v10, -v148, v94 row_newbcast:8 row_mask:0xf bank_mask:0xf
	v_fmac_f32_dpp v131, -v148, v91 row_newbcast:5 row_mask:0xf bank_mask:0xf
	v_fmac_f32_dpp v132, -v148, v96 row_newbcast:10 row_mask:0xf bank_mask:0xf
	v_fmac_f32_dpp v133, -v148, v97 row_newbcast:11 row_mask:0xf bank_mask:0xf
	v_fmac_f32_dpp v131, -v148, v95 row_newbcast:9 row_mask:0xf bank_mask:0xf
	v_add_f32_e32 v20, v10, v131
	v_add_f32_e32 v21, v132, v133
	v_add_f32_e32 v86, v20, v21
	ds_read_b32 v148, v138 offset:3840
	s_waitcnt lgkmcnt(2)
	v_mul_f32_dpp v135, -v144, v87 row_newbcast:1 row_mask:0xf bank_mask:0xf
	v_mul_f32_dpp v136, -v144, v88 row_newbcast:2 row_mask:0xf bank_mask:0xf
	v_mul_f32_dpp v137, -v144, v89 row_newbcast:3 row_mask:0xf bank_mask:0xf
	v_fmac_f32_dpp v171, -v144, v86 row_newbcast:0 row_mask:0xf bank_mask:0xf
	v_fmac_f32_dpp v135, -v144, v91 row_newbcast:5 row_mask:0xf bank_mask:0xf
	v_fmac_f32_dpp v136, -v144, v92 row_newbcast:6 row_mask:0xf bank_mask:0xf
	v_fmac_f32_dpp v137, -v144, v93 row_newbcast:7 row_mask:0xf bank_mask:0xf
	v_fmac_f32_dpp v171, -v144, v90 row_newbcast:4 row_mask:0xf bank_mask:0xf
	v_fmac_f32_dpp v135, -v144, v95 row_newbcast:9 row_mask:0xf bank_mask:0xf
	v_fmac_f32_dpp v136, -v144, v96 row_newbcast:10 row_mask:0xf bank_mask:0xf
	v_fmac_f32_dpp v137, -v144, v97 row_newbcast:11 row_mask:0xf bank_mask:0xf
	v_fmac_f32_dpp v171, -v144, v94 row_newbcast:8 row_mask:0xf bank_mask:0xf
	v_add_f32_e32 v20, v171, v135
	v_add_f32_e32 v21, v136, v137
	v_add_f32_e32 v85, v20, v21
	ds_read_b32 v144, v138 offset:3648
	s_waitcnt lgkmcnt(2)
	v_fmac_f32_dpp v170, -v140, v86 row_newbcast:4 row_mask:0xf bank_mask:0xf
	v_mul_f32_dpp v131, -v140, v87 row_newbcast:5 row_mask:0xf bank_mask:0xf
	v_mul_f32_dpp v132, -v140, v88 row_newbcast:6 row_mask:0xf bank_mask:0xf
	v_mul_f32_dpp v133, -v140, v85 row_newbcast:3 row_mask:0xf bank_mask:0xf
	v_fmac_f32_dpp v170, -v140, v90 row_newbcast:8 row_mask:0xf bank_mask:0xf
	v_fmac_f32_dpp v131, -v140, v91 row_newbcast:9 row_mask:0xf bank_mask:0xf
	v_fmac_f32_dpp v132, -v140, v92 row_newbcast:10 row_mask:0xf bank_mask:0xf
	v_fmac_f32_dpp v133, -v140, v89 row_newbcast:7 row_mask:0xf bank_mask:0xf
	v_fmac_f32_dpp v170, -v140, v94 row_newbcast:12 row_mask:0xf bank_mask:0xf
	v_fmac_f32_dpp v131, -v140, v95 row_newbcast:13 row_mask:0xf bank_mask:0xf
	v_fmac_f32_dpp v132, -v140, v96 row_newbcast:14 row_mask:0xf bank_mask:0xf
	v_fmac_f32_dpp v133, -v140, v93 row_newbcast:11 row_mask:0xf bank_mask:0xf
	s_nop 1
	v_fmac_f32_dpp v133, -v140, v97 row_newbcast:15 row_mask:0xf bank_mask:0xf
	v_add_f32_e32 v20, v170, v131
	v_add_f32_e32 v21, v132, v133
	v_add_f32_e32 v84, v20, v21
	ds_read_b32 v140, v138 offset:3456
	s_waitcnt lgkmcnt(2)
	v_mul_f32_dpp v137, -v148, v85 row_newbcast:3 row_mask:0xf bank_mask:0xf
	v_fmac_f32_dpp v169, -v148, v86 row_newbcast:4 row_mask:0xf bank_mask:0xf
	v_mul_f32_dpp v135, -v148, v87 row_newbcast:5 row_mask:0xf bank_mask:0xf
	v_mul_f32_dpp v136, -v148, v84 row_newbcast:2 row_mask:0xf bank_mask:0xf
	v_fmac_f32_dpp v137, -v148, v89 row_newbcast:7 row_mask:0xf bank_mask:0xf
	v_fmac_f32_dpp v169, -v148, v90 row_newbcast:8 row_mask:0xf bank_mask:0xf
	v_fmac_f32_dpp v135, -v148, v91 row_newbcast:9 row_mask:0xf bank_mask:0xf
	v_fmac_f32_dpp v136, -v148, v88 row_newbcast:6 row_mask:0xf bank_mask:0xf
	v_fmac_f32_dpp v137, -v148, v93 row_newbcast:11 row_mask:0xf bank_mask:0xf
	v_fmac_f32_dpp v169, -v148, v94 row_newbcast:12 row_mask:0xf bank_mask:0xf
	v_fmac_f32_dpp v135, -v148, v95 row_newbcast:13 row_mask:0xf bank_mask:0xf
	v_fmac_f32_dpp v136, -v148, v92 row_newbcast:10 row_mask:0xf bank_mask:0xf
	v_fmac_f32_dpp v137, -v148, v97 row_newbcast:15 row_mask:0xf bank_mask:0xf
	s_nop 0
	v_fmac_f32_dpp v136, -v148, v96 row_newbcast:14 row_mask:0xf bank_mask:0xf
	v_add_f32_e32 v20, v169, v135
	v_add_f32_e32 v21, v136, v137
	v_add_f32_e32 v83, v20, v21
	ds_read_b32 v148, v138 offset:3248
	ds_read_b32 v149, v138 offset:3312
	s_waitcnt lgkmcnt(3)
	v_mul_f32_dpp v132, -v144, v84 row_newbcast:2 row_mask:0xf bank_mask:0xf
	v_mul_f32_dpp v133, -v144, v85 row_newbcast:3 row_mask:0xf bank_mask:0xf
	v_fmac_f32_dpp v168, -v144, v86 row_newbcast:4 row_mask:0xf bank_mask:0xf
	v_mul_f32_dpp v131, -v144, v83 row_newbcast:1 row_mask:0xf bank_mask:0xf
	v_fmac_f32_dpp v132, -v144, v88 row_newbcast:6 row_mask:0xf bank_mask:0xf
	v_fmac_f32_dpp v133, -v144, v89 row_newbcast:7 row_mask:0xf bank_mask:0xf
	v_fmac_f32_dpp v168, -v144, v90 row_newbcast:8 row_mask:0xf bank_mask:0xf
	v_fmac_f32_dpp v131, -v144, v87 row_newbcast:5 row_mask:0xf bank_mask:0xf
	v_fmac_f32_dpp v132, -v144, v92 row_newbcast:10 row_mask:0xf bank_mask:0xf
	v_fmac_f32_dpp v133, -v144, v93 row_newbcast:11 row_mask:0xf bank_mask:0xf
	v_fmac_f32_dpp v168, -v144, v94 row_newbcast:12 row_mask:0xf bank_mask:0xf
	v_fmac_f32_dpp v131, -v144, v91 row_newbcast:9 row_mask:0xf bank_mask:0xf
	v_fmac_f32_dpp v132, -v144, v96 row_newbcast:14 row_mask:0xf bank_mask:0xf
	v_fmac_f32_dpp v133, -v144, v97 row_newbcast:15 row_mask:0xf bank_mask:0xf
	v_fmac_f32_dpp v131, -v144, v95 row_newbcast:13 row_mask:0xf bank_mask:0xf
	v_add_f32_e32 v20, v168, v131
	v_add_f32_e32 v21, v132, v133
	v_add_f32_e32 v82, v20, v21
	ds_read_b32 v144, v138 offset:3040
	ds_read_b32 v145, v138 offset:3104
	s_waitcnt lgkmcnt(4)
	v_mul_f32_dpp v135, -v140, v83 row_newbcast:1 row_mask:0xf bank_mask:0xf
	v_mul_f32_dpp v136, -v140, v84 row_newbcast:2 row_mask:0xf bank_mask:0xf
	v_mul_f32_dpp v137, -v140, v85 row_newbcast:3 row_mask:0xf bank_mask:0xf
	v_fmac_f32_dpp v9, -v140, v82 row_newbcast:0 row_mask:0xf bank_mask:0xf
	v_fmac_f32_dpp v135, -v140, v87 row_newbcast:5 row_mask:0xf bank_mask:0xf
	v_fmac_f32_dpp v136, -v140, v88 row_newbcast:6 row_mask:0xf bank_mask:0xf
	v_fmac_f32_dpp v137, -v140, v89 row_newbcast:7 row_mask:0xf bank_mask:0xf
	v_fmac_f32_dpp v9, -v140, v86 row_newbcast:4 row_mask:0xf bank_mask:0xf
	v_fmac_f32_dpp v135, -v140, v91 row_newbcast:9 row_mask:0xf bank_mask:0xf
	v_fmac_f32_dpp v136, -v140, v92 row_newbcast:10 row_mask:0xf bank_mask:0xf
	v_fmac_f32_dpp v137, -v140, v93 row_newbcast:11 row_mask:0xf bank_mask:0xf
	v_fmac_f32_dpp v9, -v140, v90 row_newbcast:8 row_mask:0xf bank_mask:0xf
	v_fmac_f32_dpp v135, -v140, v95 row_newbcast:13 row_mask:0xf bank_mask:0xf
	v_fmac_f32_dpp v136, -v140, v96 row_newbcast:14 row_mask:0xf bank_mask:0xf
	v_fmac_f32_dpp v137, -v140, v97 row_newbcast:15 row_mask:0xf bank_mask:0xf
	v_fmac_f32_dpp v9, -v140, v94 row_newbcast:12 row_mask:0xf bank_mask:0xf
	v_add_f32_e32 v20, v9, v135
	v_add_f32_e32 v21, v136, v137
	v_add_f32_e32 v81, v20, v21
	ds_read_b32 v140, v138 offset:2832
	ds_read_b32 v141, v138 offset:2896
	s_waitcnt lgkmcnt(4)
	v_fmac_f32_dpp v8, -v148, v82 row_newbcast:4 row_mask:0xf bank_mask:0xf
	v_mul_f32_dpp v131, -v148, v83 row_newbcast:5 row_mask:0xf bank_mask:0xf
	v_mul_f32_dpp v132, -v148, v84 row_newbcast:6 row_mask:0xf bank_mask:0xf
	v_mul_f32_dpp v133, -v148, v81 row_newbcast:3 row_mask:0xf bank_mask:0xf
	v_fmac_f32_dpp v8, -v148, v86 row_newbcast:8 row_mask:0xf bank_mask:0xf
	v_fmac_f32_dpp v131, -v148, v87 row_newbcast:9 row_mask:0xf bank_mask:0xf
	v_fmac_f32_dpp v132, -v148, v88 row_newbcast:10 row_mask:0xf bank_mask:0xf
	v_fmac_f32_dpp v133, -v148, v85 row_newbcast:7 row_mask:0xf bank_mask:0xf
	v_fmac_f32_dpp v8, -v148, v90 row_newbcast:12 row_mask:0xf bank_mask:0xf
	v_fmac_f32_dpp v131, -v148, v91 row_newbcast:13 row_mask:0xf bank_mask:0xf
	v_fmac_f32_dpp v132, -v148, v92 row_newbcast:14 row_mask:0xf bank_mask:0xf
	v_fmac_f32_dpp v133, -v148, v89 row_newbcast:11 row_mask:0xf bank_mask:0xf
	v_fmac_f32_dpp v8, -v149, v94 row_newbcast:0 row_mask:0xf bank_mask:0xf
	v_fmac_f32_dpp v131, -v149, v95 row_newbcast:1 row_mask:0xf bank_mask:0xf
	v_fmac_f32_dpp v132, -v149, v96 row_newbcast:2 row_mask:0xf bank_mask:0xf
	v_fmac_f32_dpp v133, -v148, v93 row_newbcast:15 row_mask:0xf bank_mask:0xf
	s_nop 1
	v_fmac_f32_dpp v133, -v149, v97 row_newbcast:3 row_mask:0xf bank_mask:0xf
	v_add_f32_e32 v20, v8, v131
	v_add_f32_e32 v21, v132, v133
	v_add_f32_e32 v80, v20, v21
	ds_read_b32 v148, v138 offset:2624
	ds_read_b32 v149, v138 offset:2688
	s_waitcnt lgkmcnt(4)
	v_mul_f32_dpp v137, -v144, v81 row_newbcast:3 row_mask:0xf bank_mask:0xf
	v_fmac_f32_dpp v7, -v144, v82 row_newbcast:4 row_mask:0xf bank_mask:0xf
	v_mul_f32_dpp v135, -v144, v83 row_newbcast:5 row_mask:0xf bank_mask:0xf
	v_mul_f32_dpp v136, -v144, v80 row_newbcast:2 row_mask:0xf bank_mask:0xf
	v_fmac_f32_dpp v137, -v144, v85 row_newbcast:7 row_mask:0xf bank_mask:0xf
	v_fmac_f32_dpp v7, -v144, v86 row_newbcast:8 row_mask:0xf bank_mask:0xf
	v_fmac_f32_dpp v135, -v144, v87 row_newbcast:9 row_mask:0xf bank_mask:0xf
	v_fmac_f32_dpp v136, -v144, v84 row_newbcast:6 row_mask:0xf bank_mask:0xf
	v_fmac_f32_dpp v137, -v144, v89 row_newbcast:11 row_mask:0xf bank_mask:0xf
	v_fmac_f32_dpp v7, -v144, v90 row_newbcast:12 row_mask:0xf bank_mask:0xf
	v_fmac_f32_dpp v135, -v144, v91 row_newbcast:13 row_mask:0xf bank_mask:0xf
	v_fmac_f32_dpp v136, -v144, v88 row_newbcast:10 row_mask:0xf bank_mask:0xf
	v_fmac_f32_dpp v137, -v144, v93 row_newbcast:15 row_mask:0xf bank_mask:0xf
	v_fmac_f32_dpp v7, -v145, v94 row_newbcast:0 row_mask:0xf bank_mask:0xf
	v_fmac_f32_dpp v135, -v145, v95 row_newbcast:1 row_mask:0xf bank_mask:0xf
	v_fmac_f32_dpp v136, -v144, v92 row_newbcast:14 row_mask:0xf bank_mask:0xf
	v_fmac_f32_dpp v137, -v145, v97 row_newbcast:3 row_mask:0xf bank_mask:0xf
	s_nop 0
	v_fmac_f32_dpp v136, -v145, v96 row_newbcast:2 row_mask:0xf bank_mask:0xf
	v_add_f32_e32 v20, v7, v135
	v_add_f32_e32 v21, v136, v137
	v_add_f32_e32 v79, v20, v21
	ds_read_b32 v144, v138 offset:2400
	ds_read_b32 v145, v138 offset:2464
	s_waitcnt lgkmcnt(4)
	v_mul_f32_dpp v132, -v140, v80 row_newbcast:2 row_mask:0xf bank_mask:0xf
	v_mul_f32_dpp v133, -v140, v81 row_newbcast:3 row_mask:0xf bank_mask:0xf
	v_fmac_f32_dpp v6, -v140, v82 row_newbcast:4 row_mask:0xf bank_mask:0xf
	v_mul_f32_dpp v131, -v140, v79 row_newbcast:1 row_mask:0xf bank_mask:0xf
	v_fmac_f32_dpp v132, -v140, v84 row_newbcast:6 row_mask:0xf bank_mask:0xf
	v_fmac_f32_dpp v133, -v140, v85 row_newbcast:7 row_mask:0xf bank_mask:0xf
	v_fmac_f32_dpp v6, -v140, v86 row_newbcast:8 row_mask:0xf bank_mask:0xf
	v_fmac_f32_dpp v131, -v140, v83 row_newbcast:5 row_mask:0xf bank_mask:0xf
	v_fmac_f32_dpp v132, -v140, v88 row_newbcast:10 row_mask:0xf bank_mask:0xf
	v_fmac_f32_dpp v133, -v140, v89 row_newbcast:11 row_mask:0xf bank_mask:0xf
	v_fmac_f32_dpp v6, -v140, v90 row_newbcast:12 row_mask:0xf bank_mask:0xf
	v_fmac_f32_dpp v131, -v140, v87 row_newbcast:9 row_mask:0xf bank_mask:0xf
	v_fmac_f32_dpp v132, -v140, v92 row_newbcast:14 row_mask:0xf bank_mask:0xf
	v_fmac_f32_dpp v133, -v140, v93 row_newbcast:15 row_mask:0xf bank_mask:0xf
	v_fmac_f32_dpp v6, -v141, v94 row_newbcast:0 row_mask:0xf bank_mask:0xf
	v_fmac_f32_dpp v131, -v140, v91 row_newbcast:13 row_mask:0xf bank_mask:0xf
	v_fmac_f32_dpp v132, -v141, v96 row_newbcast:2 row_mask:0xf bank_mask:0xf
	v_fmac_f32_dpp v133, -v141, v97 row_newbcast:3 row_mask:0xf bank_mask:0xf
	v_fmac_f32_dpp v131, -v141, v95 row_newbcast:1 row_mask:0xf bank_mask:0xf
	v_add_f32_e32 v20, v6, v131
	v_add_f32_e32 v21, v132, v133
	v_add_f32_e32 v78, v20, v21
	ds_read_b32 v140, v138 offset:2176
	ds_read_b32 v141, v138 offset:2240
	s_waitcnt lgkmcnt(4)
	v_mul_f32_dpp v135, -v148, v79 row_newbcast:1 row_mask:0xf bank_mask:0xf
	v_mul_f32_dpp v136, -v148, v80 row_newbcast:2 row_mask:0xf bank_mask:0xf
	v_mul_f32_dpp v137, -v148, v81 row_newbcast:3 row_mask:0xf bank_mask:0xf
	v_fmac_f32_dpp v167, -v148, v78 row_newbcast:0 row_mask:0xf bank_mask:0xf
	v_fmac_f32_dpp v135, -v148, v83 row_newbcast:5 row_mask:0xf bank_mask:0xf
	v_fmac_f32_dpp v136, -v148, v84 row_newbcast:6 row_mask:0xf bank_mask:0xf
	v_fmac_f32_dpp v137, -v148, v85 row_newbcast:7 row_mask:0xf bank_mask:0xf
	v_fmac_f32_dpp v167, -v148, v82 row_newbcast:4 row_mask:0xf bank_mask:0xf
	v_fmac_f32_dpp v135, -v148, v87 row_newbcast:9 row_mask:0xf bank_mask:0xf
	v_fmac_f32_dpp v136, -v148, v88 row_newbcast:10 row_mask:0xf bank_mask:0xf
	v_fmac_f32_dpp v137, -v148, v89 row_newbcast:11 row_mask:0xf bank_mask:0xf
	v_fmac_f32_dpp v167, -v148, v86 row_newbcast:8 row_mask:0xf bank_mask:0xf
	v_fmac_f32_dpp v135, -v148, v91 row_newbcast:13 row_mask:0xf bank_mask:0xf
	v_fmac_f32_dpp v136, -v148, v92 row_newbcast:14 row_mask:0xf bank_mask:0xf
	v_fmac_f32_dpp v137, -v148, v93 row_newbcast:15 row_mask:0xf bank_mask:0xf
	v_fmac_f32_dpp v167, -v148, v90 row_newbcast:12 row_mask:0xf bank_mask:0xf
	v_fmac_f32_dpp v135, -v149, v95 row_newbcast:1 row_mask:0xf bank_mask:0xf
	v_fmac_f32_dpp v136, -v149, v96 row_newbcast:2 row_mask:0xf bank_mask:0xf
	v_fmac_f32_dpp v137, -v149, v97 row_newbcast:3 row_mask:0xf bank_mask:0xf
	v_fmac_f32_dpp v167, -v149, v94 row_newbcast:0 row_mask:0xf bank_mask:0xf
	v_add_f32_e32 v20, v167, v135
	v_add_f32_e32 v21, v136, v137
	v_add_f32_e32 v77, v20, v21
	ds_read_b32 v148, v138 offset:1952
	ds_read_b32 v149, v138 offset:2016
	s_waitcnt lgkmcnt(4)
	v_fmac_f32_dpp v166, -v144, v78 row_newbcast:4 row_mask:0xf bank_mask:0xf
	v_mul_f32_dpp v131, -v144, v79 row_newbcast:5 row_mask:0xf bank_mask:0xf
	v_mul_f32_dpp v132, -v144, v80 row_newbcast:6 row_mask:0xf bank_mask:0xf
	v_mul_f32_dpp v133, -v144, v77 row_newbcast:3 row_mask:0xf bank_mask:0xf
	v_fmac_f32_dpp v166, -v144, v82 row_newbcast:8 row_mask:0xf bank_mask:0xf
	v_fmac_f32_dpp v131, -v144, v83 row_newbcast:9 row_mask:0xf bank_mask:0xf
	v_fmac_f32_dpp v132, -v144, v84 row_newbcast:10 row_mask:0xf bank_mask:0xf
	v_fmac_f32_dpp v133, -v144, v81 row_newbcast:7 row_mask:0xf bank_mask:0xf
	v_fmac_f32_dpp v166, -v144, v86 row_newbcast:12 row_mask:0xf bank_mask:0xf
	v_fmac_f32_dpp v131, -v144, v87 row_newbcast:13 row_mask:0xf bank_mask:0xf
	v_fmac_f32_dpp v132, -v144, v88 row_newbcast:14 row_mask:0xf bank_mask:0xf
	v_fmac_f32_dpp v133, -v144, v85 row_newbcast:11 row_mask:0xf bank_mask:0xf
	v_fmac_f32_dpp v166, -v145, v90 row_newbcast:0 row_mask:0xf bank_mask:0xf
	v_fmac_f32_dpp v131, -v145, v91 row_newbcast:1 row_mask:0xf bank_mask:0xf
	v_fmac_f32_dpp v132, -v145, v92 row_newbcast:2 row_mask:0xf bank_mask:0xf
	v_fmac_f32_dpp v133, -v144, v89 row_newbcast:15 row_mask:0xf bank_mask:0xf
	v_fmac_f32_dpp v166, -v145, v94 row_newbcast:4 row_mask:0xf bank_mask:0xf
	v_fmac_f32_dpp v131, -v145, v95 row_newbcast:5 row_mask:0xf bank_mask:0xf
	v_fmac_f32_dpp v132, -v145, v96 row_newbcast:6 row_mask:0xf bank_mask:0xf
	v_fmac_f32_dpp v133, -v145, v93 row_newbcast:3 row_mask:0xf bank_mask:0xf
	s_nop 1
	v_fmac_f32_dpp v133, -v145, v97 row_newbcast:7 row_mask:0xf bank_mask:0xf
	v_add_f32_e32 v20, v166, v131
	v_add_f32_e32 v21, v132, v133
	v_add_f32_e32 v76, v20, v21
	ds_read_b32 v144, v138 offset:1728
	ds_read_b32 v145, v138 offset:1792
	s_waitcnt lgkmcnt(4)
	v_mul_f32_dpp v137, -v140, v77 row_newbcast:3 row_mask:0xf bank_mask:0xf
	v_fmac_f32_dpp v165, -v140, v78 row_newbcast:4 row_mask:0xf bank_mask:0xf
	v_mul_f32_dpp v135, -v140, v79 row_newbcast:5 row_mask:0xf bank_mask:0xf
	v_mul_f32_dpp v136, -v140, v76 row_newbcast:2 row_mask:0xf bank_mask:0xf
	v_fmac_f32_dpp v137, -v140, v81 row_newbcast:7 row_mask:0xf bank_mask:0xf
	v_fmac_f32_dpp v165, -v140, v82 row_newbcast:8 row_mask:0xf bank_mask:0xf
	v_fmac_f32_dpp v135, -v140, v83 row_newbcast:9 row_mask:0xf bank_mask:0xf
	v_fmac_f32_dpp v136, -v140, v80 row_newbcast:6 row_mask:0xf bank_mask:0xf
	v_fmac_f32_dpp v137, -v140, v85 row_newbcast:11 row_mask:0xf bank_mask:0xf
	v_fmac_f32_dpp v165, -v140, v86 row_newbcast:12 row_mask:0xf bank_mask:0xf
	v_fmac_f32_dpp v135, -v140, v87 row_newbcast:13 row_mask:0xf bank_mask:0xf
	v_fmac_f32_dpp v136, -v140, v84 row_newbcast:10 row_mask:0xf bank_mask:0xf
	v_fmac_f32_dpp v137, -v140, v89 row_newbcast:15 row_mask:0xf bank_mask:0xf
	v_fmac_f32_dpp v165, -v141, v90 row_newbcast:0 row_mask:0xf bank_mask:0xf
	v_fmac_f32_dpp v135, -v141, v91 row_newbcast:1 row_mask:0xf bank_mask:0xf
	v_fmac_f32_dpp v136, -v140, v88 row_newbcast:14 row_mask:0xf bank_mask:0xf
	v_fmac_f32_dpp v137, -v141, v93 row_newbcast:3 row_mask:0xf bank_mask:0xf
	v_fmac_f32_dpp v165, -v141, v94 row_newbcast:4 row_mask:0xf bank_mask:0xf
	v_fmac_f32_dpp v135, -v141, v95 row_newbcast:5 row_mask:0xf bank_mask:0xf
	v_fmac_f32_dpp v136, -v141, v92 row_newbcast:2 row_mask:0xf bank_mask:0xf
	v_fmac_f32_dpp v137, -v141, v97 row_newbcast:7 row_mask:0xf bank_mask:0xf
	s_nop 0
	v_fmac_f32_dpp v136, -v141, v96 row_newbcast:6 row_mask:0xf bank_mask:0xf
	v_add_f32_e32 v20, v165, v135
	v_add_f32_e32 v21, v136, v137
	v_add_f32_e32 v75, v20, v21
	ds_read_b32 v140, v138 offset:1488
	ds_read_b32 v141, v138 offset:1552
	s_waitcnt lgkmcnt(4)
	v_mul_f32_dpp v132, -v148, v76 row_newbcast:2 row_mask:0xf bank_mask:0xf
	v_mul_f32_dpp v133, -v148, v77 row_newbcast:3 row_mask:0xf bank_mask:0xf
	v_fmac_f32_dpp v164, -v148, v78 row_newbcast:4 row_mask:0xf bank_mask:0xf
	v_mul_f32_dpp v131, -v148, v75 row_newbcast:1 row_mask:0xf bank_mask:0xf
	v_fmac_f32_dpp v132, -v148, v80 row_newbcast:6 row_mask:0xf bank_mask:0xf
	v_fmac_f32_dpp v133, -v148, v81 row_newbcast:7 row_mask:0xf bank_mask:0xf
	v_fmac_f32_dpp v164, -v148, v82 row_newbcast:8 row_mask:0xf bank_mask:0xf
	v_fmac_f32_dpp v131, -v148, v79 row_newbcast:5 row_mask:0xf bank_mask:0xf
	v_fmac_f32_dpp v132, -v148, v84 row_newbcast:10 row_mask:0xf bank_mask:0xf
	v_fmac_f32_dpp v133, -v148, v85 row_newbcast:11 row_mask:0xf bank_mask:0xf
	v_fmac_f32_dpp v164, -v148, v86 row_newbcast:12 row_mask:0xf bank_mask:0xf
	v_fmac_f32_dpp v131, -v148, v83 row_newbcast:9 row_mask:0xf bank_mask:0xf
	v_fmac_f32_dpp v132, -v148, v88 row_newbcast:14 row_mask:0xf bank_mask:0xf
	v_fmac_f32_dpp v133, -v148, v89 row_newbcast:15 row_mask:0xf bank_mask:0xf
	v_fmac_f32_dpp v164, -v149, v90 row_newbcast:0 row_mask:0xf bank_mask:0xf
	v_fmac_f32_dpp v131, -v148, v87 row_newbcast:13 row_mask:0xf bank_mask:0xf
	v_fmac_f32_dpp v132, -v149, v92 row_newbcast:2 row_mask:0xf bank_mask:0xf
	v_fmac_f32_dpp v133, -v149, v93 row_newbcast:3 row_mask:0xf bank_mask:0xf
	v_fmac_f32_dpp v164, -v149, v94 row_newbcast:4 row_mask:0xf bank_mask:0xf
	v_fmac_f32_dpp v131, -v149, v91 row_newbcast:1 row_mask:0xf bank_mask:0xf
	v_fmac_f32_dpp v132, -v149, v96 row_newbcast:6 row_mask:0xf bank_mask:0xf
	v_fmac_f32_dpp v133, -v149, v97 row_newbcast:7 row_mask:0xf bank_mask:0xf
	v_fmac_f32_dpp v131, -v149, v95 row_newbcast:5 row_mask:0xf bank_mask:0xf
	v_add_f32_e32 v20, v164, v131
	v_add_f32_e32 v21, v132, v133
	v_add_f32_e32 v74, v20, v21
	ds_read_b32 v148, v138 offset:1248
	ds_read_b32 v149, v138 offset:1312
	s_waitcnt lgkmcnt(4)
	v_mul_f32_dpp v135, -v144, v75 row_newbcast:1 row_mask:0xf bank_mask:0xf
	v_mul_f32_dpp v136, -v144, v76 row_newbcast:2 row_mask:0xf bank_mask:0xf
	v_mul_f32_dpp v137, -v144, v77 row_newbcast:3 row_mask:0xf bank_mask:0xf
	v_fmac_f32_dpp v5, -v144, v74 row_newbcast:0 row_mask:0xf bank_mask:0xf
	v_fmac_f32_dpp v135, -v144, v79 row_newbcast:5 row_mask:0xf bank_mask:0xf
	v_fmac_f32_dpp v136, -v144, v80 row_newbcast:6 row_mask:0xf bank_mask:0xf
	v_fmac_f32_dpp v137, -v144, v81 row_newbcast:7 row_mask:0xf bank_mask:0xf
	v_fmac_f32_dpp v5, -v144, v78 row_newbcast:4 row_mask:0xf bank_mask:0xf
	v_fmac_f32_dpp v135, -v144, v83 row_newbcast:9 row_mask:0xf bank_mask:0xf
	v_fmac_f32_dpp v136, -v144, v84 row_newbcast:10 row_mask:0xf bank_mask:0xf
	v_fmac_f32_dpp v137, -v144, v85 row_newbcast:11 row_mask:0xf bank_mask:0xf
	v_fmac_f32_dpp v5, -v144, v82 row_newbcast:8 row_mask:0xf bank_mask:0xf
	v_fmac_f32_dpp v135, -v144, v87 row_newbcast:13 row_mask:0xf bank_mask:0xf
	v_fmac_f32_dpp v136, -v144, v88 row_newbcast:14 row_mask:0xf bank_mask:0xf
	v_fmac_f32_dpp v137, -v144, v89 row_newbcast:15 row_mask:0xf bank_mask:0xf
	v_fmac_f32_dpp v5, -v144, v86 row_newbcast:12 row_mask:0xf bank_mask:0xf
	v_fmac_f32_dpp v135, -v145, v91 row_newbcast:1 row_mask:0xf bank_mask:0xf
	v_fmac_f32_dpp v136, -v145, v92 row_newbcast:2 row_mask:0xf bank_mask:0xf
	v_fmac_f32_dpp v137, -v145, v93 row_newbcast:3 row_mask:0xf bank_mask:0xf
	v_fmac_f32_dpp v5, -v145, v90 row_newbcast:0 row_mask:0xf bank_mask:0xf
	v_fmac_f32_dpp v135, -v145, v95 row_newbcast:5 row_mask:0xf bank_mask:0xf
	v_fmac_f32_dpp v136, -v145, v96 row_newbcast:6 row_mask:0xf bank_mask:0xf
	v_fmac_f32_dpp v137, -v145, v97 row_newbcast:7 row_mask:0xf bank_mask:0xf
	v_fmac_f32_dpp v5, -v145, v94 row_newbcast:4 row_mask:0xf bank_mask:0xf
	v_add_f32_e32 v20, v5, v135
	v_add_f32_e32 v21, v136, v137
	v_add_f32_e32 v73, v20, v21
	ds_read_b32 v144, v138 offset:1008
	ds_read_b32 v145, v138 offset:1072
	s_waitcnt lgkmcnt(4)
	v_fmac_f32_dpp v4, -v140, v74 row_newbcast:4 row_mask:0xf bank_mask:0xf
	v_mul_f32_dpp v131, -v140, v75 row_newbcast:5 row_mask:0xf bank_mask:0xf
	v_mul_f32_dpp v132, -v140, v76 row_newbcast:6 row_mask:0xf bank_mask:0xf
	v_mul_f32_dpp v133, -v140, v73 row_newbcast:3 row_mask:0xf bank_mask:0xf
	v_fmac_f32_dpp v4, -v140, v78 row_newbcast:8 row_mask:0xf bank_mask:0xf
	v_fmac_f32_dpp v131, -v140, v79 row_newbcast:9 row_mask:0xf bank_mask:0xf
	v_fmac_f32_dpp v132, -v140, v80 row_newbcast:10 row_mask:0xf bank_mask:0xf
	v_fmac_f32_dpp v133, -v140, v77 row_newbcast:7 row_mask:0xf bank_mask:0xf
	v_fmac_f32_dpp v4, -v140, v82 row_newbcast:12 row_mask:0xf bank_mask:0xf
	v_fmac_f32_dpp v131, -v140, v83 row_newbcast:13 row_mask:0xf bank_mask:0xf
	v_fmac_f32_dpp v132, -v140, v84 row_newbcast:14 row_mask:0xf bank_mask:0xf
	v_fmac_f32_dpp v133, -v140, v81 row_newbcast:11 row_mask:0xf bank_mask:0xf
	v_fmac_f32_dpp v4, -v141, v86 row_newbcast:0 row_mask:0xf bank_mask:0xf
	v_fmac_f32_dpp v131, -v141, v87 row_newbcast:1 row_mask:0xf bank_mask:0xf
	v_fmac_f32_dpp v132, -v141, v88 row_newbcast:2 row_mask:0xf bank_mask:0xf
	v_fmac_f32_dpp v133, -v140, v85 row_newbcast:15 row_mask:0xf bank_mask:0xf
	v_fmac_f32_dpp v4, -v141, v90 row_newbcast:4 row_mask:0xf bank_mask:0xf
	v_fmac_f32_dpp v131, -v141, v91 row_newbcast:5 row_mask:0xf bank_mask:0xf
	v_fmac_f32_dpp v132, -v141, v92 row_newbcast:6 row_mask:0xf bank_mask:0xf
	v_fmac_f32_dpp v133, -v141, v89 row_newbcast:3 row_mask:0xf bank_mask:0xf
	v_fmac_f32_dpp v4, -v141, v94 row_newbcast:8 row_mask:0xf bank_mask:0xf
	v_fmac_f32_dpp v131, -v141, v95 row_newbcast:9 row_mask:0xf bank_mask:0xf
	v_fmac_f32_dpp v132, -v141, v96 row_newbcast:10 row_mask:0xf bank_mask:0xf
	v_fmac_f32_dpp v133, -v141, v93 row_newbcast:7 row_mask:0xf bank_mask:0xf
	s_nop 1
	v_fmac_f32_dpp v133, -v141, v97 row_newbcast:11 row_mask:0xf bank_mask:0xf
	v_add_f32_e32 v20, v4, v131
	v_add_f32_e32 v21, v132, v133
	v_add_f32_e32 v72, v20, v21
	ds_read_b32 v140, v138 offset:768
	ds_read_b32 v141, v138 offset:832
	s_waitcnt lgkmcnt(4)
	v_mul_f32_dpp v137, -v148, v73 row_newbcast:3 row_mask:0xf bank_mask:0xf
	v_fmac_f32_dpp v3, -v148, v74 row_newbcast:4 row_mask:0xf bank_mask:0xf
	v_mul_f32_dpp v135, -v148, v75 row_newbcast:5 row_mask:0xf bank_mask:0xf
	v_mul_f32_dpp v136, -v148, v72 row_newbcast:2 row_mask:0xf bank_mask:0xf
	v_fmac_f32_dpp v137, -v148, v77 row_newbcast:7 row_mask:0xf bank_mask:0xf
	v_fmac_f32_dpp v3, -v148, v78 row_newbcast:8 row_mask:0xf bank_mask:0xf
	v_fmac_f32_dpp v135, -v148, v79 row_newbcast:9 row_mask:0xf bank_mask:0xf
	v_fmac_f32_dpp v136, -v148, v76 row_newbcast:6 row_mask:0xf bank_mask:0xf
	v_fmac_f32_dpp v137, -v148, v81 row_newbcast:11 row_mask:0xf bank_mask:0xf
	v_fmac_f32_dpp v3, -v148, v82 row_newbcast:12 row_mask:0xf bank_mask:0xf
	v_fmac_f32_dpp v135, -v148, v83 row_newbcast:13 row_mask:0xf bank_mask:0xf
	v_fmac_f32_dpp v136, -v148, v80 row_newbcast:10 row_mask:0xf bank_mask:0xf
	v_fmac_f32_dpp v137, -v148, v85 row_newbcast:15 row_mask:0xf bank_mask:0xf
	v_fmac_f32_dpp v3, -v149, v86 row_newbcast:0 row_mask:0xf bank_mask:0xf
	v_fmac_f32_dpp v135, -v149, v87 row_newbcast:1 row_mask:0xf bank_mask:0xf
	v_fmac_f32_dpp v136, -v148, v84 row_newbcast:14 row_mask:0xf bank_mask:0xf
	v_fmac_f32_dpp v137, -v149, v89 row_newbcast:3 row_mask:0xf bank_mask:0xf
	v_fmac_f32_dpp v3, -v149, v90 row_newbcast:4 row_mask:0xf bank_mask:0xf
	v_fmac_f32_dpp v135, -v149, v91 row_newbcast:5 row_mask:0xf bank_mask:0xf
	v_fmac_f32_dpp v136, -v149, v88 row_newbcast:2 row_mask:0xf bank_mask:0xf
	v_fmac_f32_dpp v137, -v149, v93 row_newbcast:7 row_mask:0xf bank_mask:0xf
	v_fmac_f32_dpp v3, -v149, v94 row_newbcast:8 row_mask:0xf bank_mask:0xf
	v_fmac_f32_dpp v135, -v149, v95 row_newbcast:9 row_mask:0xf bank_mask:0xf
	v_fmac_f32_dpp v136, -v149, v92 row_newbcast:6 row_mask:0xf bank_mask:0xf
	v_fmac_f32_dpp v137, -v149, v97 row_newbcast:11 row_mask:0xf bank_mask:0xf
	s_nop 0
	v_fmac_f32_dpp v136, -v149, v96 row_newbcast:10 row_mask:0xf bank_mask:0xf
	v_add_f32_e32 v20, v3, v135
	v_add_f32_e32 v21, v136, v137
	v_add_f32_e32 v71, v20, v21
	ds_read_b32 v148, v138 offset:512
	ds_read_b32 v149, v138 offset:576
	s_waitcnt lgkmcnt(4)
	v_mul_f32_dpp v132, -v144, v72 row_newbcast:2 row_mask:0xf bank_mask:0xf
	v_mul_f32_dpp v133, -v144, v73 row_newbcast:3 row_mask:0xf bank_mask:0xf
	v_fmac_f32_dpp v2, -v144, v74 row_newbcast:4 row_mask:0xf bank_mask:0xf
	v_mul_f32_dpp v131, -v144, v71 row_newbcast:1 row_mask:0xf bank_mask:0xf
	v_fmac_f32_dpp v132, -v144, v76 row_newbcast:6 row_mask:0xf bank_mask:0xf
	v_fmac_f32_dpp v133, -v144, v77 row_newbcast:7 row_mask:0xf bank_mask:0xf
	v_fmac_f32_dpp v2, -v144, v78 row_newbcast:8 row_mask:0xf bank_mask:0xf
	v_fmac_f32_dpp v131, -v144, v75 row_newbcast:5 row_mask:0xf bank_mask:0xf
	v_fmac_f32_dpp v132, -v144, v80 row_newbcast:10 row_mask:0xf bank_mask:0xf
	v_fmac_f32_dpp v133, -v144, v81 row_newbcast:11 row_mask:0xf bank_mask:0xf
	v_fmac_f32_dpp v2, -v144, v82 row_newbcast:12 row_mask:0xf bank_mask:0xf
	v_fmac_f32_dpp v131, -v144, v79 row_newbcast:9 row_mask:0xf bank_mask:0xf
	v_fmac_f32_dpp v132, -v144, v84 row_newbcast:14 row_mask:0xf bank_mask:0xf
	v_fmac_f32_dpp v133, -v144, v85 row_newbcast:15 row_mask:0xf bank_mask:0xf
	v_fmac_f32_dpp v2, -v145, v86 row_newbcast:0 row_mask:0xf bank_mask:0xf
	v_fmac_f32_dpp v131, -v144, v83 row_newbcast:13 row_mask:0xf bank_mask:0xf
	v_fmac_f32_dpp v132, -v145, v88 row_newbcast:2 row_mask:0xf bank_mask:0xf
	v_fmac_f32_dpp v133, -v145, v89 row_newbcast:3 row_mask:0xf bank_mask:0xf
	v_fmac_f32_dpp v2, -v145, v90 row_newbcast:4 row_mask:0xf bank_mask:0xf
	v_fmac_f32_dpp v131, -v145, v87 row_newbcast:1 row_mask:0xf bank_mask:0xf
	v_fmac_f32_dpp v132, -v145, v92 row_newbcast:6 row_mask:0xf bank_mask:0xf
	v_fmac_f32_dpp v133, -v145, v93 row_newbcast:7 row_mask:0xf bank_mask:0xf
	v_fmac_f32_dpp v2, -v145, v94 row_newbcast:8 row_mask:0xf bank_mask:0xf
	v_fmac_f32_dpp v131, -v145, v91 row_newbcast:5 row_mask:0xf bank_mask:0xf
	v_fmac_f32_dpp v132, -v145, v96 row_newbcast:10 row_mask:0xf bank_mask:0xf
	v_fmac_f32_dpp v133, -v145, v97 row_newbcast:11 row_mask:0xf bank_mask:0xf
	v_fmac_f32_dpp v131, -v145, v95 row_newbcast:9 row_mask:0xf bank_mask:0xf
	v_add_f32_e32 v20, v2, v131
	v_add_f32_e32 v21, v132, v133
	v_add_f32_e32 v70, v20, v21
	ds_read_b32 v144, v138 offset:256
	ds_read_b32 v145, v138 offset:320
	s_waitcnt lgkmcnt(4)
	v_mul_f32_dpp v135, -v140, v71 row_newbcast:1 row_mask:0xf bank_mask:0xf
	v_mul_f32_dpp v136, -v140, v72 row_newbcast:2 row_mask:0xf bank_mask:0xf
	v_mul_f32_dpp v137, -v140, v73 row_newbcast:3 row_mask:0xf bank_mask:0xf
	v_fmac_f32_dpp v163, -v140, v70 row_newbcast:0 row_mask:0xf bank_mask:0xf
	v_fmac_f32_dpp v135, -v140, v75 row_newbcast:5 row_mask:0xf bank_mask:0xf
	v_fmac_f32_dpp v136, -v140, v76 row_newbcast:6 row_mask:0xf bank_mask:0xf
	v_fmac_f32_dpp v137, -v140, v77 row_newbcast:7 row_mask:0xf bank_mask:0xf
	v_fmac_f32_dpp v163, -v140, v74 row_newbcast:4 row_mask:0xf bank_mask:0xf
	v_fmac_f32_dpp v135, -v140, v79 row_newbcast:9 row_mask:0xf bank_mask:0xf
	v_fmac_f32_dpp v136, -v140, v80 row_newbcast:10 row_mask:0xf bank_mask:0xf
	v_fmac_f32_dpp v137, -v140, v81 row_newbcast:11 row_mask:0xf bank_mask:0xf
	v_fmac_f32_dpp v163, -v140, v78 row_newbcast:8 row_mask:0xf bank_mask:0xf
	v_fmac_f32_dpp v135, -v140, v83 row_newbcast:13 row_mask:0xf bank_mask:0xf
	v_fmac_f32_dpp v136, -v140, v84 row_newbcast:14 row_mask:0xf bank_mask:0xf
	v_fmac_f32_dpp v137, -v140, v85 row_newbcast:15 row_mask:0xf bank_mask:0xf
	v_fmac_f32_dpp v163, -v140, v82 row_newbcast:12 row_mask:0xf bank_mask:0xf
	v_fmac_f32_dpp v135, -v141, v87 row_newbcast:1 row_mask:0xf bank_mask:0xf
	v_fmac_f32_dpp v136, -v141, v88 row_newbcast:2 row_mask:0xf bank_mask:0xf
	v_fmac_f32_dpp v137, -v141, v89 row_newbcast:3 row_mask:0xf bank_mask:0xf
	v_fmac_f32_dpp v163, -v141, v86 row_newbcast:0 row_mask:0xf bank_mask:0xf
	v_fmac_f32_dpp v135, -v141, v91 row_newbcast:5 row_mask:0xf bank_mask:0xf
	v_fmac_f32_dpp v136, -v141, v92 row_newbcast:6 row_mask:0xf bank_mask:0xf
	v_fmac_f32_dpp v137, -v141, v93 row_newbcast:7 row_mask:0xf bank_mask:0xf
	v_fmac_f32_dpp v163, -v141, v90 row_newbcast:4 row_mask:0xf bank_mask:0xf
	v_fmac_f32_dpp v135, -v141, v95 row_newbcast:9 row_mask:0xf bank_mask:0xf
	v_fmac_f32_dpp v136, -v141, v96 row_newbcast:10 row_mask:0xf bank_mask:0xf
	v_fmac_f32_dpp v137, -v141, v97 row_newbcast:11 row_mask:0xf bank_mask:0xf
	v_fmac_f32_dpp v163, -v141, v94 row_newbcast:8 row_mask:0xf bank_mask:0xf
	v_add_f32_e32 v20, v163, v135
	v_add_f32_e32 v21, v136, v137
	v_add_f32_e32 v69, v20, v21
	ds_read_b32 v140, v138 offset:0
	ds_read_b32 v141, v138 offset:64
	s_waitcnt lgkmcnt(4)
	v_fmac_f32_dpp v162, -v148, v70 row_newbcast:4 row_mask:0xf bank_mask:0xf
	v_mul_f32_dpp v131, -v148, v71 row_newbcast:5 row_mask:0xf bank_mask:0xf
	v_mul_f32_dpp v132, -v148, v72 row_newbcast:6 row_mask:0xf bank_mask:0xf
	v_mul_f32_dpp v133, -v148, v69 row_newbcast:3 row_mask:0xf bank_mask:0xf
	v_fmac_f32_dpp v162, -v148, v74 row_newbcast:8 row_mask:0xf bank_mask:0xf
	v_fmac_f32_dpp v131, -v148, v75 row_newbcast:9 row_mask:0xf bank_mask:0xf
	v_fmac_f32_dpp v132, -v148, v76 row_newbcast:10 row_mask:0xf bank_mask:0xf
	v_fmac_f32_dpp v133, -v148, v73 row_newbcast:7 row_mask:0xf bank_mask:0xf
	v_fmac_f32_dpp v162, -v148, v78 row_newbcast:12 row_mask:0xf bank_mask:0xf
	v_fmac_f32_dpp v131, -v148, v79 row_newbcast:13 row_mask:0xf bank_mask:0xf
	v_fmac_f32_dpp v132, -v148, v80 row_newbcast:14 row_mask:0xf bank_mask:0xf
	v_fmac_f32_dpp v133, -v148, v77 row_newbcast:11 row_mask:0xf bank_mask:0xf
	v_fmac_f32_dpp v162, -v149, v82 row_newbcast:0 row_mask:0xf bank_mask:0xf
	v_fmac_f32_dpp v131, -v149, v83 row_newbcast:1 row_mask:0xf bank_mask:0xf
	v_fmac_f32_dpp v132, -v149, v84 row_newbcast:2 row_mask:0xf bank_mask:0xf
	v_fmac_f32_dpp v133, -v148, v81 row_newbcast:15 row_mask:0xf bank_mask:0xf
	v_fmac_f32_dpp v162, -v149, v86 row_newbcast:4 row_mask:0xf bank_mask:0xf
	v_fmac_f32_dpp v131, -v149, v87 row_newbcast:5 row_mask:0xf bank_mask:0xf
	v_fmac_f32_dpp v132, -v149, v88 row_newbcast:6 row_mask:0xf bank_mask:0xf
	v_fmac_f32_dpp v133, -v149, v85 row_newbcast:3 row_mask:0xf bank_mask:0xf
	v_fmac_f32_dpp v162, -v149, v90 row_newbcast:8 row_mask:0xf bank_mask:0xf
	v_fmac_f32_dpp v131, -v149, v91 row_newbcast:9 row_mask:0xf bank_mask:0xf
	v_fmac_f32_dpp v132, -v149, v92 row_newbcast:10 row_mask:0xf bank_mask:0xf
	v_fmac_f32_dpp v133, -v149, v89 row_newbcast:7 row_mask:0xf bank_mask:0xf
	v_fmac_f32_dpp v162, -v149, v94 row_newbcast:12 row_mask:0xf bank_mask:0xf
	v_fmac_f32_dpp v131, -v149, v95 row_newbcast:13 row_mask:0xf bank_mask:0xf
	v_fmac_f32_dpp v132, -v149, v96 row_newbcast:14 row_mask:0xf bank_mask:0xf
	v_fmac_f32_dpp v133, -v149, v93 row_newbcast:11 row_mask:0xf bank_mask:0xf
	s_nop 1
	v_fmac_f32_dpp v133, -v149, v97 row_newbcast:15 row_mask:0xf bank_mask:0xf
	v_add_f32_e32 v20, v162, v131
	v_add_f32_e32 v21, v132, v133
	v_add_f32_e32 v68, v20, v21
	s_waitcnt lgkmcnt(2)
	v_mul_f32_dpp v137, -v144, v69 row_newbcast:3 row_mask:0xf bank_mask:0xf
	v_fmac_f32_dpp v161, -v144, v70 row_newbcast:4 row_mask:0xf bank_mask:0xf
	v_mul_f32_dpp v135, -v144, v71 row_newbcast:5 row_mask:0xf bank_mask:0xf
	v_mul_f32_dpp v136, -v144, v68 row_newbcast:2 row_mask:0xf bank_mask:0xf
	v_fmac_f32_dpp v137, -v144, v73 row_newbcast:7 row_mask:0xf bank_mask:0xf
	v_fmac_f32_dpp v161, -v144, v74 row_newbcast:8 row_mask:0xf bank_mask:0xf
	v_fmac_f32_dpp v135, -v144, v75 row_newbcast:9 row_mask:0xf bank_mask:0xf
	v_fmac_f32_dpp v136, -v144, v72 row_newbcast:6 row_mask:0xf bank_mask:0xf
	v_fmac_f32_dpp v137, -v144, v77 row_newbcast:11 row_mask:0xf bank_mask:0xf
	v_fmac_f32_dpp v161, -v144, v78 row_newbcast:12 row_mask:0xf bank_mask:0xf
	v_fmac_f32_dpp v135, -v144, v79 row_newbcast:13 row_mask:0xf bank_mask:0xf
	v_fmac_f32_dpp v136, -v144, v76 row_newbcast:10 row_mask:0xf bank_mask:0xf
	v_fmac_f32_dpp v137, -v144, v81 row_newbcast:15 row_mask:0xf bank_mask:0xf
	v_fmac_f32_dpp v161, -v145, v82 row_newbcast:0 row_mask:0xf bank_mask:0xf
	v_fmac_f32_dpp v135, -v145, v83 row_newbcast:1 row_mask:0xf bank_mask:0xf
	v_fmac_f32_dpp v136, -v144, v80 row_newbcast:14 row_mask:0xf bank_mask:0xf
	v_fmac_f32_dpp v137, -v145, v85 row_newbcast:3 row_mask:0xf bank_mask:0xf
	v_fmac_f32_dpp v161, -v145, v86 row_newbcast:4 row_mask:0xf bank_mask:0xf
	v_fmac_f32_dpp v135, -v145, v87 row_newbcast:5 row_mask:0xf bank_mask:0xf
	v_fmac_f32_dpp v136, -v145, v84 row_newbcast:2 row_mask:0xf bank_mask:0xf
	v_fmac_f32_dpp v137, -v145, v89 row_newbcast:7 row_mask:0xf bank_mask:0xf
	v_fmac_f32_dpp v161, -v145, v90 row_newbcast:8 row_mask:0xf bank_mask:0xf
	v_fmac_f32_dpp v135, -v145, v91 row_newbcast:9 row_mask:0xf bank_mask:0xf
	v_fmac_f32_dpp v136, -v145, v88 row_newbcast:6 row_mask:0xf bank_mask:0xf
	v_fmac_f32_dpp v137, -v145, v93 row_newbcast:11 row_mask:0xf bank_mask:0xf
	v_fmac_f32_dpp v161, -v145, v94 row_newbcast:12 row_mask:0xf bank_mask:0xf
	v_fmac_f32_dpp v135, -v145, v95 row_newbcast:13 row_mask:0xf bank_mask:0xf
	v_fmac_f32_dpp v136, -v145, v92 row_newbcast:10 row_mask:0xf bank_mask:0xf
	v_fmac_f32_dpp v137, -v145, v97 row_newbcast:15 row_mask:0xf bank_mask:0xf
	s_nop 0
	v_fmac_f32_dpp v136, -v145, v96 row_newbcast:14 row_mask:0xf bank_mask:0xf
	v_add_f32_e32 v20, v161, v135
	v_add_f32_e32 v21, v136, v137
	v_add_f32_e32 v67, v20, v21
	s_waitcnt lgkmcnt(0)
	v_mul_f32_dpp v132, -v140, v68 row_newbcast:2 row_mask:0xf bank_mask:0xf
	v_mul_f32_dpp v133, -v140, v69 row_newbcast:3 row_mask:0xf bank_mask:0xf
	v_fmac_f32_dpp v160, -v140, v70 row_newbcast:4 row_mask:0xf bank_mask:0xf
	v_mul_f32_dpp v131, -v140, v67 row_newbcast:1 row_mask:0xf bank_mask:0xf
	v_fmac_f32_dpp v132, -v140, v72 row_newbcast:6 row_mask:0xf bank_mask:0xf
	v_fmac_f32_dpp v133, -v140, v73 row_newbcast:7 row_mask:0xf bank_mask:0xf
	v_fmac_f32_dpp v160, -v140, v74 row_newbcast:8 row_mask:0xf bank_mask:0xf
	v_fmac_f32_dpp v131, -v140, v71 row_newbcast:5 row_mask:0xf bank_mask:0xf
	v_fmac_f32_dpp v132, -v140, v76 row_newbcast:10 row_mask:0xf bank_mask:0xf
	v_fmac_f32_dpp v133, -v140, v77 row_newbcast:11 row_mask:0xf bank_mask:0xf
	v_fmac_f32_dpp v160, -v140, v78 row_newbcast:12 row_mask:0xf bank_mask:0xf
	v_fmac_f32_dpp v131, -v140, v75 row_newbcast:9 row_mask:0xf bank_mask:0xf
	v_fmac_f32_dpp v132, -v140, v80 row_newbcast:14 row_mask:0xf bank_mask:0xf
	v_fmac_f32_dpp v133, -v140, v81 row_newbcast:15 row_mask:0xf bank_mask:0xf
	v_fmac_f32_dpp v160, -v141, v82 row_newbcast:0 row_mask:0xf bank_mask:0xf
	v_fmac_f32_dpp v131, -v140, v79 row_newbcast:13 row_mask:0xf bank_mask:0xf
	v_fmac_f32_dpp v132, -v141, v84 row_newbcast:2 row_mask:0xf bank_mask:0xf
	v_fmac_f32_dpp v133, -v141, v85 row_newbcast:3 row_mask:0xf bank_mask:0xf
	v_fmac_f32_dpp v160, -v141, v86 row_newbcast:4 row_mask:0xf bank_mask:0xf
	v_fmac_f32_dpp v131, -v141, v83 row_newbcast:1 row_mask:0xf bank_mask:0xf
	v_fmac_f32_dpp v132, -v141, v88 row_newbcast:6 row_mask:0xf bank_mask:0xf
	v_fmac_f32_dpp v133, -v141, v89 row_newbcast:7 row_mask:0xf bank_mask:0xf
	v_fmac_f32_dpp v160, -v141, v90 row_newbcast:8 row_mask:0xf bank_mask:0xf
	v_fmac_f32_dpp v131, -v141, v87 row_newbcast:5 row_mask:0xf bank_mask:0xf
	v_fmac_f32_dpp v132, -v141, v92 row_newbcast:10 row_mask:0xf bank_mask:0xf
	v_fmac_f32_dpp v133, -v141, v93 row_newbcast:11 row_mask:0xf bank_mask:0xf
	v_fmac_f32_dpp v160, -v141, v94 row_newbcast:12 row_mask:0xf bank_mask:0xf
	v_fmac_f32_dpp v131, -v141, v91 row_newbcast:9 row_mask:0xf bank_mask:0xf
	v_fmac_f32_dpp v132, -v141, v96 row_newbcast:14 row_mask:0xf bank_mask:0xf
	v_fmac_f32_dpp v133, -v141, v97 row_newbcast:15 row_mask:0xf bank_mask:0xf
	v_fmac_f32_dpp v131, -v141, v95 row_newbcast:13 row_mask:0xf bank_mask:0xf
	v_add_f32_e32 v20, v160, v131
	v_add_f32_e32 v21, v132, v133
	v_add_f32_e32 v66, v20, v21
	v_mov_b32_e32 v19, s5
	v_and_b32_e32 v20, 31, v1
	v_lshlrev_b32_e32 v20, 4, v20
	v_cmp_lt_u32_e32 vcc, 31, v1
	s_nop 1
	v_cndmask_b32_e32 v21, 0, v193, vcc
	v_or_b32_e32 v21, v21, v20
	v_add_u32_e32 v20, 0x1000, v20
	ds_read_b128 v[194:197], v19 offset:0
	ds_read_b128 v[198:201], v19 offset:32
	ds_read_b128 v[202:205], v19 offset:16
	ds_read_b128 v[206:209], v19 offset:48
	ds_read_b128 v[210:213], v19 offset:64
	ds_read_b128 v[214:217], v19 offset:96
	ds_read_b128 v[218:221], v19 offset:80
	ds_read_b128 v[222:225], v19 offset:112
	s_waitcnt lgkmcnt(6)
	v_pk_mul_f32 v[2:3], v[66:67], v[194:195]
	v_pk_mul_f32 v[4:5], v[68:69], v[196:197]
	v_pk_mul_f32 v[6:7], v[74:75], v[198:199]
	v_pk_mul_f32 v[8:9], v[76:77], v[200:201]
	v_cvt_pk_bf16_f32 v10, v2, v3
	v_cvt_pk_bf16_f32 v11, v4, v5
	v_cvt_pk_bf16_f32 v12, v6, v7
	v_cvt_pk_bf16_f32 v13, v8, v9
	global_store_dwordx4 v21, v[10:13], s[6:7] sc0 sc1
	s_waitcnt lgkmcnt(4)
	v_pk_mul_f32 v[2:3], v[70:71], v[202:203]
	v_pk_mul_f32 v[4:5], v[72:73], v[204:205]
	v_pk_mul_f32 v[6:7], v[78:79], v[206:207]
	v_pk_mul_f32 v[8:9], v[80:81], v[208:209]
	v_cvt_pk_bf16_f32 v14, v2, v3
	v_cvt_pk_bf16_f32 v15, v4, v5
	v_cvt_pk_bf16_f32 v16, v6, v7
	v_cvt_pk_bf16_f32 v17, v8, v9
	global_store_dwordx4 v21, v[14:17], s[6:7] offset:512 sc0 sc1
	s_waitcnt lgkmcnt(2)
	v_pk_mul_f32 v[2:3], v[82:83], v[210:211]
	v_pk_mul_f32 v[4:5], v[84:85], v[212:213]
	v_pk_mul_f32 v[6:7], v[90:91], v[214:215]
	v_pk_mul_f32 v[8:9], v[92:93], v[216:217]
	v_cvt_pk_bf16_f32 v10, v2, v3
	v_cvt_pk_bf16_f32 v11, v4, v5
	v_cvt_pk_bf16_f32 v12, v6, v7
	v_cvt_pk_bf16_f32 v13, v8, v9
	global_store_dwordx4 v21, v[10:13], s[6:7] offset:1024 sc0 sc1
	s_waitcnt lgkmcnt(0)
	v_pk_mul_f32 v[2:3], v[86:87], v[218:219]
	v_pk_mul_f32 v[4:5], v[88:89], v[220:221]
	v_pk_mul_f32 v[6:7], v[94:95], v[222:223]
	v_pk_mul_f32 v[8:9], v[96:97], v[224:225]
	v_cvt_pk_bf16_f32 v14, v2, v3
	v_cvt_pk_bf16_f32 v15, v4, v5
	v_cvt_pk_bf16_f32 v16, v6, v7
	v_cvt_pk_bf16_f32 v17, v8, v9
	global_store_dwordx4 v21, v[14:17], s[6:7] offset:1536 sc0 sc1
	s_and_saveexec_b64 s[0:1], vcc
	s_cbranch_execz .LBB0_655
	ds_read_b128 v[194:197], v19 offset:128
	ds_read_b128 v[198:201], v19 offset:160
	ds_read_b128 v[202:205], v19 offset:144
	ds_read_b128 v[206:209], v19 offset:176
	ds_read_b128 v[210:213], v19 offset:192
	ds_read_b128 v[214:217], v19 offset:224
	ds_read_b128 v[218:221], v19 offset:208
	ds_read_b128 v[222:225], v19 offset:240
	s_waitcnt lgkmcnt(6)
	v_pk_mul_f32 v[2:3], v[98:99], v[194:195]
	v_pk_mul_f32 v[4:5], v[100:101], v[196:197]
	v_pk_mul_f32 v[6:7], v[106:107], v[198:199]
	v_pk_mul_f32 v[8:9], v[108:109], v[200:201]
	v_cvt_pk_bf16_f32 v10, v2, v3
	v_cvt_pk_bf16_f32 v11, v4, v5
	v_cvt_pk_bf16_f32 v12, v6, v7
	v_cvt_pk_bf16_f32 v13, v8, v9
	global_store_dwordx4 v20, v[10:13], s[6:7] sc0 sc1
	s_waitcnt lgkmcnt(4)
	v_pk_mul_f32 v[2:3], v[102:103], v[202:203]
	v_pk_mul_f32 v[4:5], v[104:105], v[204:205]
	v_pk_mul_f32 v[6:7], v[110:111], v[206:207]
	v_pk_mul_f32 v[8:9], v[112:113], v[208:209]
	v_cvt_pk_bf16_f32 v14, v2, v3
	v_cvt_pk_bf16_f32 v15, v4, v5
	v_cvt_pk_bf16_f32 v16, v6, v7
	v_cvt_pk_bf16_f32 v17, v8, v9
	global_store_dwordx4 v20, v[14:17], s[6:7] offset:512 sc0 sc1
	s_waitcnt lgkmcnt(2)
	v_pk_mul_f32 v[2:3], v[114:115], v[210:211]
	v_pk_mul_f32 v[4:5], v[116:117], v[212:213]
	v_pk_mul_f32 v[6:7], v[122:123], v[214:215]
	v_pk_mul_f32 v[8:9], v[124:125], v[216:217]
	v_cvt_pk_bf16_f32 v10, v2, v3
	v_cvt_pk_bf16_f32 v11, v4, v5
	v_cvt_pk_bf16_f32 v12, v6, v7
	v_cvt_pk_bf16_f32 v13, v8, v9
	global_store_dwordx4 v20, v[10:13], s[6:7] offset:1024 sc0 sc1
	s_waitcnt lgkmcnt(0)
	v_pk_mul_f32 v[2:3], v[118:119], v[218:219]
	v_pk_mul_f32 v[4:5], v[120:121], v[220:221]
	v_pk_mul_f32 v[6:7], v[126:127], v[222:223]
	v_pk_mul_f32 v[8:9], v[128:129], v[224:225]
	v_cvt_pk_bf16_f32 v14, v2, v3
	v_cvt_pk_bf16_f32 v15, v4, v5
	v_cvt_pk_bf16_f32 v16, v6, v7
	v_cvt_pk_bf16_f32 v17, v8, v9
	global_store_dwordx4 v20, v[14:17], s[6:7] offset:1536 sc0 sc1
	s_nop 1
